# GEMM K-loops: early post-MMA barrier (2 trailing MFMAs) extended to all 8 phases
# speedup vs baseline: 1.0087x; 1.0087x over previous
; #define PG8_STAGE(bufoff, gbase, voff) do { _Pragma("unroll") for (int _i = 0; _i < 2; ++_i) \
;         __builtin_amdgcn_global_load_lds((const unsigned*)((const char*)(gbase) + (voff)[_i]), (LAS unsigned*)(lds + (bufoff) + ldsw + _i * 8192), 16, 0, 0); } while (0)
; #define PG8_LDA(dst, b, h) do { _Pragma("unroll") for (int m = 0; m < 4; ++m) _Pragma("unroll") for (int k = 0; k < 2; ++k) dst[m][k] = *(const LAS bf16x8*)(lds + PG8_SA(b, h) + aoff + m * 2048 + k * 1024); } while (0)
; #define PG8_LDB(dst, b, h) do { _Pragma("unroll") for (int n = 0; n < 2; ++n) _Pragma("unroll") for (int k = 0; k < 2; ++k) dst[n][k] = *(const LAS bf16x8*)(lds + PG8_SB(b, h) + boff + n * 2048 + k * 1024); } while (0)
; #define PG8_MMA(ai, bj, At, Bt) do { __builtin_amdgcn_s_setprio(1); _Pragma("unroll") for (int m = 0; m < 4; ++m) _Pragma("unroll") for (int n = 0; n < 2; ++n) _Pragma("unroll") for (int k = 0; k < 2; ++k) \
;         acc[ai][bj][m][n] = __builtin_amdgcn_mfma_f32_16x16x32_bf16(Bt[n][k], At[m][k], acc[ai][bj][m][n], 0, 0, 0); __builtin_amdgcn_s_setprio(0); } while (0)
; #define PG8_WAIT_V(n) asm volatile("s_waitcnt vmcnt(" #n ")" ::: "memory")
; #define PG8_WAIT_L(n) asm volatile("s_waitcnt lgkmcnt(" #n ")" ::: "memory")
; template <class Epi, class Sched, int LD>
; __device__ __forceinline__ void gemm_phase(LAS unsigned char* lds, const Gemm g, const Sched& S, const Epi& E) {
;     ...
;         for (int t = 0; t < nt; t += 2) {
;             const bool last = (t == nt - 2);
;             const char* a1 = cA + (size_t)(t + 1) * kstep;
;             const char* a2 = last ? nA : cA + (size_t)(t + 2) * kstep; const char* b2 = last ? nB : cB + (size_t)(t + 2) * kstep;
;             const char* a3 = a2 + kstep; const char* b3 = b2 + kstep;
;             PG8_LDB(B0, 0, 0); PG8_SCHED; PG8_LDA(At, 0, 0); PG8_STAGE(PG8_SA(1, 1), a1 + hstep, voffA);
;             PG8_WAIT_L(8); PG8_BAR; PG8_WAIT_L(0); PG8_MMA(0, 0, At, B0); PG8_BAR; PG8_SCHED;
;             PG8_LDB(B1, 0, 1); PG8_STAGE(PG8_SB(0, 0), b2, voffB);
;             PG8_BAR; PG8_WAIT_L(0); PG8_MMA(0, 1, At, B1); PG8_BAR;
;             PG8_LDA(At, 0, 1); PG8_STAGE(PG8_SA(0, 0), a2, voffA);
;             PG8_BAR; PG8_WAIT_L(0); PG8_MMA(1, 0, At, B0); PG8_BAR; PG8_SCHED;
;             PG8_STAGE(PG8_SB(0, 1), b2 + hstep, voffB);
;             PG8_WAIT_V(6); PG8_BAR; PG8_MMA(1, 1, At, B1); PG8_BAR;
.LBB0_58:
	s_add_i32 s71, s4, 2
	s_add_u32 s48, s46, 0x4000
	s_addc_u32 s5, s47, 0
	s_cmp_eq_u32 s68, s4
	s_cselect_b32 s4, s42, s48
	s_cselect_b32 s5, s43, s5
	s_cselect_b32 s48, s44, s69
	s_cselect_b32 s49, s45, s70
	s_add_u32 s50, s4, 0x8000
	s_addc_u32 s51, s5, 0
	s_add_i32 s72, 0, 0x10000
	s_add_i32 m0, s39, 0xc000
	ds_read_b128 v[180:183], v148
	ds_read_b128 v[184:187], v148 offset:1024
	ds_read_b128 v[188:191], v148 offset:2048
	ds_read_b128 v[192:195], v148 offset:3072
	ds_read_b128 v[196:199], v148 offset:4096
	ds_read_b128 v[200:203], v148 offset:5120
	ds_read_b128 v[204:207], v148 offset:6144
	ds_read_b128 v[208:211], v148 offset:7168
	global_load_lds_dwordx4 v132, s[46:47]
	s_add_i32 m0, s39, 0xe000
	s_nop 0
	global_load_lds_dwordx4 v138, s[46:47]
	s_waitcnt lgkmcnt(8)
	s_barrier
	s_waitcnt lgkmcnt(0)
	s_setprio 0
	v_mfma_f32_16x16x32_bf16 v[128:131], v[140:143], v[180:183], v[128:131]
	v_mfma_f32_16x16x32_bf16 v[124:127], v[154:157], v[180:183], v[124:127]
	v_mfma_f32_16x16x32_bf16 v[112:115], v[140:143], v[188:191], v[112:115]
	v_mfma_f32_16x16x32_bf16 v[108:111], v[154:157], v[188:191], v[108:111]
	v_mfma_f32_16x16x32_bf16 v[96:99], v[140:143], v[196:199], v[96:99]
	v_mfma_f32_16x16x32_bf16 v[92:95], v[154:157], v[196:199], v[92:95]
	v_mfma_f32_16x16x32_bf16 v[80:83], v[140:143], v[204:207], v[80:83]
	v_mfma_f32_16x16x32_bf16 v[76:79], v[154:157], v[204:207], v[76:79]
	v_mfma_f32_16x16x32_bf16 v[128:131], v[150:153], v[184:187], v[128:131]
	v_mfma_f32_16x16x32_bf16 v[124:127], v[176:179], v[184:187], v[124:127]
	v_mfma_f32_16x16x32_bf16 v[112:115], v[150:153], v[192:195], v[112:115]
	v_mfma_f32_16x16x32_bf16 v[108:111], v[176:179], v[192:195], v[108:111]
	v_mfma_f32_16x16x32_bf16 v[96:99], v[150:153], v[200:203], v[96:99]
	v_mfma_f32_16x16x32_bf16 v[92:95], v[176:179], v[200:203], v[92:95]
	s_setprio 3
	s_barrier
	v_mfma_f32_16x16x32_bf16 v[80:83], v[150:153], v[208:211], v[80:83]
	v_mfma_f32_16x16x32_bf16 v[76:79], v[176:179], v[208:211], v[76:79]
	s_setprio 2
	s_add_i32 s74, 0, 0x14000
	s_add_i32 s72, s72, s29
	ds_read_b128 v[212:215], v228 offset:16384
	ds_read_b128 v[216:219], v228 offset:17408
	ds_read_b128 v[220:223], v228 offset:18432
	ds_read_b128 v[224:227], v228 offset:19456
	s_mov_b32 m0, s72
	s_nop 0
	global_load_lds_dwordx4 v132, s[48:49]
	s_add_i32 m0, s72, 0x2000
	s_nop 0
	global_load_lds_dwordx4 v138, s[48:49]
	s_barrier
	s_waitcnt lgkmcnt(0)
	s_setprio 0
	v_mfma_f32_16x16x32_bf16 v[120:123], v[212:215], v[180:183], v[120:123]
	v_mfma_f32_16x16x32_bf16 v[116:119], v[220:223], v[180:183], v[116:119]
	v_mfma_f32_16x16x32_bf16 v[104:107], v[212:215], v[188:191], v[104:107]
	v_mfma_f32_16x16x32_bf16 v[100:103], v[220:223], v[188:191], v[100:103]
	v_mfma_f32_16x16x32_bf16 v[88:91], v[212:215], v[196:199], v[88:91]
	v_mfma_f32_16x16x32_bf16 v[84:87], v[220:223], v[196:199], v[84:87]
	v_mfma_f32_16x16x32_bf16 v[72:75], v[212:215], v[204:207], v[72:75]
	v_mfma_f32_16x16x32_bf16 v[68:71], v[220:223], v[204:207], v[68:71]
	v_mfma_f32_16x16x32_bf16 v[120:123], v[216:219], v[184:187], v[120:123]
	v_mfma_f32_16x16x32_bf16 v[116:119], v[224:227], v[184:187], v[116:119]
	v_mfma_f32_16x16x32_bf16 v[104:107], v[216:219], v[192:195], v[104:107]
	v_mfma_f32_16x16x32_bf16 v[100:103], v[224:227], v[192:195], v[100:103]
	v_mfma_f32_16x16x32_bf16 v[88:91], v[216:219], v[200:203], v[88:91]
	v_mfma_f32_16x16x32_bf16 v[84:87], v[224:227], v[200:203], v[84:87]
	s_setprio 3
	s_mov_b32 m0, s39
	s_barrier
	v_mfma_f32_16x16x32_bf16 v[72:75], v[216:219], v[208:211], v[72:75]
	v_mfma_f32_16x16x32_bf16 v[68:71], v[224:227], v[208:211], v[68:71]
	s_setprio 2
	ds_read_b128 v[180:183], v148 offset:16384
	ds_read_b128 v[184:187], v148 offset:17408
	ds_read_b128 v[188:191], v148 offset:18432
	ds_read_b128 v[192:195], v148 offset:19456
	ds_read_b128 v[196:199], v148 offset:20480
	ds_read_b128 v[200:203], v148 offset:21504
	ds_read_b128 v[204:207], v148 offset:22528
	ds_read_b128 v[208:211], v148 offset:23552
	global_load_lds_dwordx4 v132, s[4:5]
	s_mov_b32 m0, s52
	s_nop 0
	global_load_lds_dwordx4 v138, s[4:5]
	s_waitcnt vmcnt(10)
	s_barrier
	s_waitcnt lgkmcnt(0)
	s_setprio 0
	v_mfma_f32_16x16x32_bf16 v[64:67], v[140:143], v[180:183], v[64:67]
	v_mfma_f32_16x16x32_bf16 v[60:63], v[154:157], v[180:183], v[60:63]
	v_mfma_f32_16x16x32_bf16 v[48:51], v[140:143], v[188:191], v[48:51]
	v_mfma_f32_16x16x32_bf16 v[44:47], v[154:157], v[188:191], v[44:47]
	v_mfma_f32_16x16x32_bf16 v[32:35], v[140:143], v[196:199], v[32:35]
	v_mfma_f32_16x16x32_bf16 v[28:31], v[154:157], v[196:199], v[28:31]
	v_mfma_f32_16x16x32_bf16 v[16:19], v[140:143], v[204:207], v[16:19]
	v_mfma_f32_16x16x32_bf16 v[12:15], v[154:157], v[204:207], v[12:15]
	v_mfma_f32_16x16x32_bf16 v[64:67], v[150:153], v[184:187], v[64:67]
	v_mfma_f32_16x16x32_bf16 v[60:63], v[176:179], v[184:187], v[60:63]
	v_mfma_f32_16x16x32_bf16 v[48:51], v[150:153], v[192:195], v[48:51]
	v_mfma_f32_16x16x32_bf16 v[44:47], v[176:179], v[192:195], v[44:47]
	v_mfma_f32_16x16x32_bf16 v[32:35], v[150:153], v[200:203], v[32:35]
	v_mfma_f32_16x16x32_bf16 v[28:31], v[176:179], v[200:203], v[28:31]
	s_setprio 3
	s_barrier
	v_mfma_f32_16x16x32_bf16 v[16:19], v[150:153], v[208:211], v[16:19]
	v_mfma_f32_16x16x32_bf16 v[12:15], v[176:179], v[208:211], v[12:15]
	s_setprio 2
	ds_read_b128 v[140:143], v228 offset:32768
	ds_read_b128 v[150:153], v228 offset:33792
	ds_read_b128 v[154:157], v228 offset:34816
	ds_read_b128 v[176:179], v228 offset:35840
	s_add_u32 s72, s48, 0x4000
	s_addc_u32 s73, s49, 0
	s_add_i32 s74, s74, s29
	s_mov_b32 m0, s74
	s_nop 0
	global_load_lds_dwordx4 v132, s[72:73]
	s_add_i32 m0, s74, 0x2000
	s_nop 0
	global_load_lds_dwordx4 v138, s[72:73]
	s_waitcnt vmcnt(6)
	s_barrier
; #define PG8_STAGE(bufoff, gbase, voff) do { _Pragma("unroll") for (int _i = 0; _i < 2; ++_i) \
;         __builtin_amdgcn_global_load_lds((const unsigned*)((const char*)(gbase) + (voff)[_i]), (LAS unsigned*)(lds + (bufoff) + ldsw + _i * 8192), 16, 0, 0); } while (0)
; #define PG8_LDA(dst, b, h) do { _Pragma("unroll") for (int m = 0; m < 4; ++m) _Pragma("unroll") for (int k = 0; k < 2; ++k) dst[m][k] = *(const LAS bf16x8*)(lds + PG8_SA(b, h) + aoff + m * 2048 + k * 1024); } while (0)
; #define PG8_LDB(dst, b, h) do { _Pragma("unroll") for (int n = 0; n < 2; ++n) _Pragma("unroll") for (int k = 0; k < 2; ++k) dst[n][k] = *(const LAS bf16x8*)(lds + PG8_SB(b, h) + boff + n * 2048 + k * 1024); } while (0)
; #define PG8_MMA(ai, bj, At, Bt) do { __builtin_amdgcn_s_setprio(1); _Pragma("unroll") for (int m = 0; m < 4; ++m) _Pragma("unroll") for (int n = 0; n < 2; ++n) _Pragma("unroll") for (int k = 0; k < 2; ++k) \
;         acc[ai][bj][m][n] = __builtin_amdgcn_mfma_f32_16x16x32_bf16(Bt[n][k], At[m][k], acc[ai][bj][m][n], 0, 0, 0); __builtin_amdgcn_s_setprio(0); } while (0)
; #define PG8_WAIT_V(n) asm volatile("s_waitcnt vmcnt(" #n ")" ::: "memory")
; #define PG8_WAIT_L(n) asm volatile("s_waitcnt lgkmcnt(" #n ")" ::: "memory")
; #define PG8_BAR __builtin_amdgcn_s_barrier()
; #define PG8_SCHED __builtin_amdgcn_sched_barrier(0)
; template <class Epi, class Sched, int LD>
; __device__ __forceinline__ void gemm_phase(LAS unsigned char* lds, const Gemm g, const Sched& S, const Epi& E) {
;     ...
;             PG8_WAIT_V(6); PG8_BAR; PG8_MMA(1, 1, At, B1); PG8_BAR;
;             PG8_LDB(B0, 1, 0); PG8_SCHED; PG8_LDA(At, 1, 0); PG8_STAGE(PG8_SA(0, 1), a2 + hstep, voffA);
;             PG8_WAIT_L(8); PG8_BAR; PG8_WAIT_L(0); PG8_MMA(0, 0, At, B0); PG8_BAR; PG8_SCHED;
;             PG8_LDB(B1, 1, 1); PG8_STAGE(PG8_SB(1, 0), b3, voffB);
;             PG8_BAR; PG8_WAIT_L(0); PG8_MMA(0, 1, At, B1); PG8_BAR;
;             PG8_LDA(At, 1, 1); PG8_STAGE(PG8_SA(1, 0), a3, voffA);
;             PG8_BAR; PG8_WAIT_L(0); PG8_MMA(1, 0, At, B0); PG8_BAR; PG8_SCHED;
	s_setprio 0
	v_mfma_f32_16x16x32_bf16 v[56:59], v[212:215], v[180:183], v[56:59]
	v_mfma_f32_16x16x32_bf16 v[52:55], v[220:223], v[180:183], v[52:55]
	v_mfma_f32_16x16x32_bf16 v[40:43], v[212:215], v[188:191], v[40:43]
	v_mfma_f32_16x16x32_bf16 v[36:39], v[220:223], v[188:191], v[36:39]
	v_mfma_f32_16x16x32_bf16 v[24:27], v[212:215], v[196:199], v[24:27]
	v_mfma_f32_16x16x32_bf16 v[20:23], v[220:223], v[196:199], v[20:23]
	v_mfma_f32_16x16x32_bf16 v[8:11], v[212:215], v[204:207], v[8:11]
	v_mfma_f32_16x16x32_bf16 v[4:7], v[220:223], v[204:207], v[4:7]
	v_mfma_f32_16x16x32_bf16 v[56:59], v[216:219], v[184:187], v[56:59]
	v_mfma_f32_16x16x32_bf16 v[52:55], v[224:227], v[184:187], v[52:55]
	v_mfma_f32_16x16x32_bf16 v[40:43], v[216:219], v[192:195], v[40:43]
	v_mfma_f32_16x16x32_bf16 v[36:39], v[224:227], v[192:195], v[36:39]
	v_mfma_f32_16x16x32_bf16 v[24:27], v[216:219], v[200:203], v[24:27]
	v_mfma_f32_16x16x32_bf16 v[20:23], v[224:227], v[200:203], v[20:23]
	s_setprio 3
	s_add_i32 s72, 0, 0x18000
	s_barrier
	v_mfma_f32_16x16x32_bf16 v[8:11], v[216:219], v[208:211], v[8:11]
	v_mfma_f32_16x16x32_bf16 v[4:7], v[224:227], v[208:211], v[4:7]
	s_setprio 2
	s_add_u32 s4, s4, 0x4000
	s_addc_u32 s5, s5, 0
	s_mov_b32 m0, s53
	ds_read_b128 v[180:183], v148 offset:32768
	ds_read_b128 v[184:187], v148 offset:33792
	ds_read_b128 v[188:191], v148 offset:34816
	ds_read_b128 v[192:195], v148 offset:35840
	ds_read_b128 v[196:199], v148 offset:36864
	ds_read_b128 v[200:203], v148 offset:37888
	ds_read_b128 v[204:207], v148 offset:38912
	ds_read_b128 v[208:211], v148 offset:39936
	global_load_lds_dwordx4 v132, s[4:5]
	s_mov_b32 m0, s54
	s_nop 0
	global_load_lds_dwordx4 v138, s[4:5]
	s_waitcnt lgkmcnt(8)
	s_barrier
	s_waitcnt lgkmcnt(0)
	s_setprio 0
	v_mfma_f32_16x16x32_bf16 v[128:131], v[140:143], v[180:183], v[128:131]
	v_mfma_f32_16x16x32_bf16 v[124:127], v[154:157], v[180:183], v[124:127]
	v_mfma_f32_16x16x32_bf16 v[112:115], v[140:143], v[188:191], v[112:115]
	v_mfma_f32_16x16x32_bf16 v[108:111], v[154:157], v[188:191], v[108:111]
	v_mfma_f32_16x16x32_bf16 v[96:99], v[140:143], v[196:199], v[96:99]
	v_mfma_f32_16x16x32_bf16 v[92:95], v[154:157], v[196:199], v[92:95]
	v_mfma_f32_16x16x32_bf16 v[80:83], v[140:143], v[204:207], v[80:83]
	v_mfma_f32_16x16x32_bf16 v[76:79], v[154:157], v[204:207], v[76:79]
	v_mfma_f32_16x16x32_bf16 v[128:131], v[150:153], v[184:187], v[128:131]
	v_mfma_f32_16x16x32_bf16 v[124:127], v[176:179], v[184:187], v[124:127]
	v_mfma_f32_16x16x32_bf16 v[112:115], v[150:153], v[192:195], v[112:115]
	v_mfma_f32_16x16x32_bf16 v[108:111], v[176:179], v[192:195], v[108:111]
	v_mfma_f32_16x16x32_bf16 v[96:99], v[150:153], v[200:203], v[96:99]
	v_mfma_f32_16x16x32_bf16 v[92:95], v[176:179], v[200:203], v[92:95]
	s_setprio 3
	s_barrier
	v_mfma_f32_16x16x32_bf16 v[80:83], v[150:153], v[208:211], v[80:83]
	v_mfma_f32_16x16x32_bf16 v[76:79], v[176:179], v[208:211], v[76:79]
	s_setprio 2
	s_add_i32 s73, 0, 0x1c000
	s_add_u32 s4, s48, 0x8000
	s_addc_u32 s5, s49, 0
	s_add_i32 s72, s72, s29
	ds_read_b128 v[212:215], v228 offset:49152
	ds_read_b128 v[216:219], v228 offset:50176
	ds_read_b128 v[220:223], v228 offset:51200
	ds_read_b128 v[224:227], v228 offset:52224
	s_mov_b32 m0, s72
	s_nop 0
	global_load_lds_dwordx4 v132, s[4:5]
	s_add_i32 m0, s72, 0x2000
	s_nop 0
	global_load_lds_dwordx4 v138, s[4:5]
	s_barrier
	s_waitcnt lgkmcnt(0)
	s_setprio 0
	v_mfma_f32_16x16x32_bf16 v[120:123], v[212:215], v[180:183], v[120:123]
	v_mfma_f32_16x16x32_bf16 v[116:119], v[220:223], v[180:183], v[116:119]
	v_mfma_f32_16x16x32_bf16 v[104:107], v[212:215], v[188:191], v[104:107]
	v_mfma_f32_16x16x32_bf16 v[100:103], v[220:223], v[188:191], v[100:103]
	v_mfma_f32_16x16x32_bf16 v[88:91], v[212:215], v[196:199], v[88:91]
	v_mfma_f32_16x16x32_bf16 v[84:87], v[220:223], v[196:199], v[84:87]
	v_mfma_f32_16x16x32_bf16 v[72:75], v[212:215], v[204:207], v[72:75]
	v_mfma_f32_16x16x32_bf16 v[68:71], v[220:223], v[204:207], v[68:71]
	v_mfma_f32_16x16x32_bf16 v[120:123], v[216:219], v[184:187], v[120:123]
	v_mfma_f32_16x16x32_bf16 v[116:119], v[224:227], v[184:187], v[116:119]
	v_mfma_f32_16x16x32_bf16 v[104:107], v[216:219], v[192:195], v[104:107]
	v_mfma_f32_16x16x32_bf16 v[100:103], v[224:227], v[192:195], v[100:103]
	v_mfma_f32_16x16x32_bf16 v[88:91], v[216:219], v[200:203], v[88:91]
	v_mfma_f32_16x16x32_bf16 v[84:87], v[224:227], v[200:203], v[84:87]
	s_setprio 3
	s_mov_b32 m0, s55
	s_barrier
	v_mfma_f32_16x16x32_bf16 v[72:75], v[216:219], v[208:211], v[72:75]
	v_mfma_f32_16x16x32_bf16 v[68:71], v[224:227], v[208:211], v[68:71]
	s_setprio 2
	ds_read_b128 v[180:183], v148 offset:49152
	ds_read_b128 v[184:187], v148 offset:50176
	ds_read_b128 v[188:191], v148 offset:51200
	ds_read_b128 v[192:195], v148 offset:52224
	ds_read_b128 v[196:199], v148 offset:53248
	ds_read_b128 v[200:203], v148 offset:54272
	ds_read_b128 v[204:207], v148 offset:55296
	ds_read_b128 v[208:211], v148 offset:56320
	global_load_lds_dwordx4 v132, s[50:51]
	s_mov_b32 m0, s56
	s_nop 0
	global_load_lds_dwordx4 v138, s[50:51]
	s_waitcnt vmcnt(10)
	s_barrier
	s_waitcnt lgkmcnt(0)
	s_setprio 0
	v_mfma_f32_16x16x32_bf16 v[64:67], v[140:143], v[180:183], v[64:67]
	v_mfma_f32_16x16x32_bf16 v[60:63], v[154:157], v[180:183], v[60:63]
	v_mfma_f32_16x16x32_bf16 v[48:51], v[140:143], v[188:191], v[48:51]
	v_mfma_f32_16x16x32_bf16 v[44:47], v[154:157], v[188:191], v[44:47]
	v_mfma_f32_16x16x32_bf16 v[32:35], v[140:143], v[196:199], v[32:35]
	v_mfma_f32_16x16x32_bf16 v[28:31], v[154:157], v[196:199], v[28:31]
	v_mfma_f32_16x16x32_bf16 v[16:19], v[140:143], v[204:207], v[16:19]
	v_mfma_f32_16x16x32_bf16 v[12:15], v[154:157], v[204:207], v[12:15]
	v_mfma_f32_16x16x32_bf16 v[64:67], v[150:153], v[184:187], v[64:67]
	v_mfma_f32_16x16x32_bf16 v[60:63], v[176:179], v[184:187], v[60:63]
	v_mfma_f32_16x16x32_bf16 v[48:51], v[150:153], v[192:195], v[48:51]
	v_mfma_f32_16x16x32_bf16 v[44:47], v[176:179], v[192:195], v[44:47]
	v_mfma_f32_16x16x32_bf16 v[32:35], v[150:153], v[200:203], v[32:35]
	v_mfma_f32_16x16x32_bf16 v[28:31], v[176:179], v[200:203], v[28:31]
	s_setprio 3
	s_barrier
; #define PG8_STAGE(bufoff, gbase, voff) do { _Pragma("unroll") for (int _i = 0; _i < 2; ++_i) \
;         __builtin_amdgcn_global_load_lds((const unsigned*)((const char*)(gbase) + (voff)[_i]), (LAS unsigned*)(lds + (bufoff) + ldsw + _i * 8192), 16, 0, 0); } while (0)
; #define PG8_MMA(ai, bj, At, Bt) do { __builtin_amdgcn_s_setprio(1); _Pragma("unroll") for (int m = 0; m < 4; ++m) _Pragma("unroll") for (int n = 0; n < 2; ++n) _Pragma("unroll") for (int k = 0; k < 2; ++k) \
;         acc[ai][bj][m][n] = __builtin_amdgcn_mfma_f32_16x16x32_bf16(Bt[n][k], At[m][k], acc[ai][bj][m][n], 0, 0, 0); __builtin_amdgcn_s_setprio(0); } while (0)
; #define PG8_WAIT_V(n) asm volatile("s_waitcnt vmcnt(" #n ")" ::: "memory")
; #define PG8_WAIT_L(n) asm volatile("s_waitcnt lgkmcnt(" #n ")" ::: "memory")
; #define PG8_BAR __builtin_amdgcn_s_barrier()
; #define PG8_SCHED __builtin_amdgcn_sched_barrier(0)
;     __device__ __forceinline__ void operator()(const f32x4 (&acc)[2][2][4][2], const Unit& u, int wr, int wc, int fr, int fq) const {
;     ...
;         } else {
;             float* base = PART + (size_t)u.part * (512 * 2048);
; #pragma unroll
;             for (int ai = 0; ai < 2; ++ai)
; #pragma unroll
;                 for (int m = 0; m < 4; ++m) {
;                     float* rowp = base + (size_t)(row0 - 8192 + ai * HALF + m * 16) * D_MODEL + col0;
; #pragma unroll
;                     for (int bj = 0; bj < 2; ++bj)
; #pragma unroll
;                         for (int n = 0; n < 2; ++n) *(f32x4*)(rowp + bj * HALF + n * 16) = acc[ai][bj][m][n];
;                 }
;         }
; template <class Epi, class Sched, int LD>
; __device__ __forceinline__ void gemm_phase(LAS unsigned char* lds, const Gemm g, const Sched& S, const Epi& E) {
;     ...
;             PG8_BAR; PG8_WAIT_L(0); PG8_MMA(1, 0, At, B0); PG8_BAR; PG8_SCHED;
;             PG8_STAGE(PG8_SB(1, 1), b3 + hstep, voffB);
;             PG8_WAIT_V(6); PG8_BAR; PG8_MMA(1, 1, At, B1); PG8_BAR;
	v_mfma_f32_16x16x32_bf16 v[16:19], v[150:153], v[208:211], v[16:19]
	v_mfma_f32_16x16x32_bf16 v[12:15], v[176:179], v[208:211], v[12:15]
	s_setprio 2
	ds_read_b128 v[140:143], v228
	ds_read_b128 v[150:153], v228 offset:1024
	ds_read_b128 v[154:157], v228 offset:2048
	ds_read_b128 v[176:179], v228 offset:3072
	s_add_u32 s4, s48, 0xc000
	s_addc_u32 s5, s49, 0
	s_add_i32 s48, s73, s29
	s_mov_b32 m0, s48
	s_nop 0
	global_load_lds_dwordx4 v132, s[4:5]
	s_add_i32 m0, s48, 0x2000
	s_nop 0
	global_load_lds_dwordx4 v138, s[4:5]
	s_waitcnt vmcnt(6)
	s_barrier
	s_setprio 0
	v_mfma_f32_16x16x32_bf16 v[56:59], v[212:215], v[180:183], v[56:59]
	v_mfma_f32_16x16x32_bf16 v[52:55], v[220:223], v[180:183], v[52:55]
	v_mfma_f32_16x16x32_bf16 v[40:43], v[212:215], v[188:191], v[40:43]
	v_mfma_f32_16x16x32_bf16 v[36:39], v[220:223], v[188:191], v[36:39]
	v_mfma_f32_16x16x32_bf16 v[24:27], v[212:215], v[196:199], v[24:27]
	v_mfma_f32_16x16x32_bf16 v[20:23], v[220:223], v[196:199], v[20:23]
	v_mfma_f32_16x16x32_bf16 v[8:11], v[212:215], v[204:207], v[8:11]
	v_mfma_f32_16x16x32_bf16 v[4:7], v[220:223], v[204:207], v[4:7]
	v_mfma_f32_16x16x32_bf16 v[56:59], v[216:219], v[184:187], v[56:59]
	v_mfma_f32_16x16x32_bf16 v[52:55], v[224:227], v[184:187], v[52:55]
	v_mfma_f32_16x16x32_bf16 v[40:43], v[216:219], v[192:195], v[40:43]
	v_mfma_f32_16x16x32_bf16 v[36:39], v[224:227], v[192:195], v[36:39]
	v_mfma_f32_16x16x32_bf16 v[24:27], v[216:219], v[200:203], v[24:27]
	v_mfma_f32_16x16x32_bf16 v[20:23], v[224:227], v[200:203], v[20:23]
	s_setprio 3
	s_add_u32 s46, s46, 0x10000
	s_addc_u32 s47, s47, 0
	s_add_u32 s69, s69, 0x10000
	s_addc_u32 s70, s70, 0
	s_cmp_ge_i32 s71, s65
	s_mov_b32 s4, s71
	s_barrier
	v_mfma_f32_16x16x32_bf16 v[8:11], v[216:219], v[208:211], v[8:11]
	v_mfma_f32_16x16x32_bf16 v[4:7], v[224:227], v[208:211], v[4:7]
	s_setprio 2
	s_cbranch_scc0 .LBB0_58
	s_setprio 0
	v_lshl_add_u32 v142, s67, 8, v137
	v_lshl_or_b32 v140, s66, 8, v147
	s_mov_b64 s[4:5], -1
	s_cmp_gt_i32 s18, -1
	v_ashrrev_i32_e32 v141, 31, v140
	v_ashrrev_i32_e32 v143, 31, v142
	s_cbranch_scc0 .LBB0_61
	s_lshl_b64 s[4:5], s[18:19], 22
	v_readlane_b32 s18, v252, 10
	s_add_u32 s4, s18, s4
	v_readlane_b32 s18, v252, 11
	s_addc_u32 s5, s18, s5
	v_lshl_add_u64 v[144:145], v[140:141], 2, s[4:5]
	v_lshlrev_b64 v[150:151], 13, v[142:143]
	s_brev_b32 s4, 63
	v_lshl_add_u64 v[144:145], v[144:145], 0, v[150:151]
	s_mov_b32 s5, -1
	v_lshl_add_u64 v[150:151], v[144:145], 0, s[4:5]
	s_brev_b32 s4, 63
	v_add_co_u32_e32 v152, vcc, s4, v144
	s_mov_b32 s4, 0xfc020000
	s_nop 0
	v_addc_co_u32_e32 v153, vcc, -1, v145, vcc
	s_mov_b32 s5, -1
	global_store_dwordx4 v[152:153], v[128:131], off
	global_store_dwordx4 v[150:151], v[124:127], off offset:64
	global_store_dwordx4 v[150:151], v[120:123], off offset:512
	global_store_dwordx4 v[150:151], v[116:119], off offset:576
	v_lshl_add_u64 v[150:151], v[144:145], 0, s[4:5]
	s_mov_b32 s4, 0xfc020000
	v_add_co_u32_e32 v152, vcc, s4, v144
	s_mov_b32 s4, 0xfc040000
	s_nop 0
	v_addc_co_u32_e32 v153, vcc, -1, v145, vcc
	s_mov_b32 s5, -1
	global_store_dwordx4 v[152:153], v[112:115], off
	global_store_dwordx4 v[150:151], v[108:111], off offset:64
	global_store_dwordx4 v[150:151], v[104:107], off offset:512
	global_store_dwordx4 v[150:151], v[100:103], off offset:576
	v_lshl_add_u64 v[150:151], v[144:145], 0, s[4:5]
	s_mov_b32 s4, 0xfc040000
	v_add_co_u32_e32 v152, vcc, s4, v144
	s_mov_b32 s4, 0xfc060000
	s_nop 0
	v_addc_co_u32_e32 v153, vcc, -1, v145, vcc
	s_mov_b32 s5, -1
	global_store_dwordx4 v[152:153], v[96:99], off
	global_store_dwordx4 v[150:151], v[92:95], off offset:64
	global_store_dwordx4 v[150:151], v[88:91], off offset:512
	global_store_dwordx4 v[150:151], v[84:87], off offset:576
	v_lshl_add_u64 v[150:151], v[144:145], 0, s[4:5]
	s_mov_b32 s4, 0xfc060000
	v_add_co_u32_e32 v152, vcc, s4, v144
	s_mov_b32 s4, 0xfc100000
	s_nop 0
	v_addc_co_u32_e32 v153, vcc, -1, v145, vcc
	s_mov_b32 s5, -1
	global_store_dwordx4 v[152:153], v[80:83], off
	global_store_dwordx4 v[150:151], v[76:79], off offset:64
	global_store_dwordx4 v[150:151], v[72:75], off offset:512
	global_store_dwordx4 v[150:151], v[68:71], off offset:576
	v_lshl_add_u64 v[150:151], v[144:145], 0, s[4:5]
	s_mov_b32 s4, 0xfc100000
	v_add_co_u32_e32 v152, vcc, s4, v144
	s_mov_b32 s4, 0xfc120000
	s_nop 0
	v_addc_co_u32_e32 v153, vcc, -1, v145, vcc
	s_mov_b32 s5, -1
	global_store_dwordx4 v[152:153], v[64:67], off
	global_store_dwordx4 v[150:151], v[60:63], off offset:64
	global_store_dwordx4 v[150:151], v[56:59], off offset:512
	global_store_dwordx4 v[150:151], v[52:55], off offset:576
	v_lshl_add_u64 v[150:151], v[144:145], 0, s[4:5]
	s_mov_b32 s4, 0xfc120000
	v_add_co_u32_e32 v152, vcc, s4, v144
	s_mov_b32 s4, 0xfc140000
	s_nop 0
	v_addc_co_u32_e32 v153, vcc, -1, v145, vcc
	s_mov_b32 s5, -1
	global_store_dwordx4 v[152:153], v[48:51], off
	global_store_dwordx4 v[150:151], v[44:47], off offset:64
	global_store_dwordx4 v[150:151], v[40:43], off offset:512
	global_store_dwordx4 v[150:151], v[36:39], off offset:576
	v_lshl_add_u64 v[150:151], v[144:145], 0, s[4:5]
	s_mov_b32 s4, 0xfc140000
	v_add_co_u32_e32 v152, vcc, s4, v144
	s_mov_b32 s4, 0xfc160000
	s_nop 0
	v_addc_co_u32_e32 v153, vcc, -1, v145, vcc
	s_mov_b32 s5, -1
	global_store_dwordx4 v[152:153], v[32:35], off
	global_store_dwordx4 v[150:151], v[28:31], off offset:64
	global_store_dwordx4 v[150:151], v[24:27], off offset:512
	global_store_dwordx4 v[150:151], v[20:23], off offset:576
	v_lshl_add_u64 v[150:151], v[144:145], 0, s[4:5]
	v_add_co_u32_e32 v144, vcc, 0xfc160000, v144
	s_mov_b64 s[4:5], 0
	s_nop 0
	v_addc_co_u32_e32 v145, vcc, -1, v145, vcc
	global_store_dwordx4 v[144:145], v[16:19], off
	global_store_dwordx4 v[150:151], v[12:15], off offset:64
	global_store_dwordx4 v[150:151], v[8:11], off offset:512
	global_store_dwordx4 v[150:151], v[4:7], off offset:576

; #define PG8_STAGE(bufoff, gbase, voff) do { _Pragma("unroll") for (int _i = 0; _i < 2; ++_i) \
;         __builtin_amdgcn_global_load_lds((const unsigned*)((const char*)(gbase) + (voff)[_i]), (LAS unsigned*)(lds + (bufoff) + ldsw + _i * 8192), 16, 0, 0); } while (0)
; #define PG8_LDA(dst, b, h) do { _Pragma("unroll") for (int m = 0; m < 4; ++m) _Pragma("unroll") for (int k = 0; k < 2; ++k) dst[m][k] = *(const LAS bf16x8*)(lds + PG8_SA(b, h) + aoff + m * 2048 + k * 1024); } while (0)
; #define PG8_LDB(dst, b, h) do { _Pragma("unroll") for (int n = 0; n < 2; ++n) _Pragma("unroll") for (int k = 0; k < 2; ++k) dst[n][k] = *(const LAS bf16x8*)(lds + PG8_SB(b, h) + boff + n * 2048 + k * 1024); } while (0)
; #define PG8_MMA(ai, bj, At, Bt) do { __builtin_amdgcn_s_setprio(1); _Pragma("unroll") for (int m = 0; m < 4; ++m) _Pragma("unroll") for (int n = 0; n < 2; ++n) _Pragma("unroll") for (int k = 0; k < 2; ++k) \
;         acc[ai][bj][m][n] = __builtin_amdgcn_mfma_f32_16x16x32_bf16(Bt[n][k], At[m][k], acc[ai][bj][m][n], 0, 0, 0); __builtin_amdgcn_s_setprio(0); } while (0)
; #define PG8_WAIT_V(n) asm volatile("s_waitcnt vmcnt(" #n ")" ::: "memory")
; #define PG8_WAIT_L(n) asm volatile("s_waitcnt lgkmcnt(" #n ")" ::: "memory")
; template <class Epi, class Sched, int LD>
; __device__ __forceinline__ void gemm_phase(LAS unsigned char* lds, const Gemm g, const Sched& S, const Epi& E) {
;     ...
;         for (int t = 0; t < nt; t += 2) {
;             const bool last = (t == nt - 2);
;             const char* a1 = cA + (size_t)(t + 1) * kstep;
;             const char* a2 = last ? nA : cA + (size_t)(t + 2) * kstep; const char* b2 = last ? nB : cB + (size_t)(t + 2) * kstep;
;             const char* a3 = a2 + kstep; const char* b3 = b2 + kstep;
;             PG8_LDB(B0, 0, 0); PG8_SCHED; PG8_LDA(At, 0, 0); PG8_STAGE(PG8_SA(1, 1), a1 + hstep, voffA);
;             PG8_WAIT_L(8); PG8_BAR; PG8_WAIT_L(0); PG8_MMA(0, 0, At, B0); PG8_BAR; PG8_SCHED;
;             PG8_LDB(B1, 0, 1); PG8_STAGE(PG8_SB(0, 0), b2, voffB);
;             PG8_BAR; PG8_WAIT_L(0); PG8_MMA(0, 1, At, B1); PG8_BAR;
;             PG8_LDA(At, 0, 1); PG8_STAGE(PG8_SA(0, 0), a2, voffA);
;             PG8_BAR; PG8_WAIT_L(0); PG8_MMA(1, 0, At, B0); PG8_BAR; PG8_SCHED;
;             PG8_STAGE(PG8_SB(0, 1), b2 + hstep, voffB);
;             PG8_WAIT_V(6); PG8_BAR; PG8_MMA(1, 1, At, B1); PG8_BAR;
.LBB0_501:
	s_add_u32 s4, s54, 0x4000
	s_addc_u32 s5, s55, 0
	s_cmp_eq_u32 s49, 28
	s_cselect_b32 s4, s50, s4
	s_cselect_b32 s5, s51, s5
	s_cselect_b32 s56, s40, s29
	s_cselect_b32 s57, s41, s47
	s_add_u32 s58, s4, 0x8000
	s_addc_u32 s59, s5, 0
	s_add_i32 s69, 0, 0x10000
	s_add_i32 m0, s52, 0xc000
	ds_read_b128 v[180:183], v146
	ds_read_b128 v[184:187], v146 offset:1024
	ds_read_b128 v[188:191], v146 offset:2048
	ds_read_b128 v[192:195], v146 offset:3072
	ds_read_b128 v[196:199], v146 offset:4096
	ds_read_b128 v[200:203], v146 offset:5120
	ds_read_b128 v[204:207], v146 offset:6144
	ds_read_b128 v[208:211], v146 offset:7168
	global_load_lds_dwordx4 v132, s[54:55]
	s_add_i32 m0, s52, 0xe000
	s_nop 0
	global_load_lds_dwordx4 v138, s[54:55]
	s_waitcnt lgkmcnt(8)
	s_barrier
	s_waitcnt lgkmcnt(0)
	s_setprio 0
	v_mfma_f32_16x16x32_bf16 v[128:131], v[148:151], v[180:183], v[128:131]
	v_mfma_f32_16x16x32_bf16 v[124:127], v[156:159], v[180:183], v[124:127]
	v_mfma_f32_16x16x32_bf16 v[120:123], v[148:151], v[188:191], v[120:123]
	v_mfma_f32_16x16x32_bf16 v[116:119], v[156:159], v[188:191], v[116:119]
	v_mfma_f32_16x16x32_bf16 v[104:107], v[148:151], v[196:199], v[104:107]
	v_mfma_f32_16x16x32_bf16 v[100:103], v[156:159], v[196:199], v[100:103]
	v_mfma_f32_16x16x32_bf16 v[88:91], v[148:151], v[204:207], v[88:91]
	v_mfma_f32_16x16x32_bf16 v[84:87], v[156:159], v[204:207], v[84:87]
	v_mfma_f32_16x16x32_bf16 v[128:131], v[152:155], v[184:187], v[128:131]
	v_mfma_f32_16x16x32_bf16 v[124:127], v[176:179], v[184:187], v[124:127]
	v_mfma_f32_16x16x32_bf16 v[120:123], v[152:155], v[192:195], v[120:123]
	v_mfma_f32_16x16x32_bf16 v[116:119], v[176:179], v[192:195], v[116:119]
	v_mfma_f32_16x16x32_bf16 v[104:107], v[152:155], v[200:203], v[104:107]
	v_mfma_f32_16x16x32_bf16 v[100:103], v[176:179], v[200:203], v[100:103]
	s_setprio 3
	s_barrier
	v_mfma_f32_16x16x32_bf16 v[88:91], v[152:155], v[208:211], v[88:91]
	v_mfma_f32_16x16x32_bf16 v[84:87], v[176:179], v[208:211], v[84:87]
	s_setprio 2
	s_add_i32 s72, 0, 0x14000
	s_add_i32 s69, s69, s39
	ds_read_b128 v[212:215], v228 offset:16384
	ds_read_b128 v[216:219], v228 offset:17408
	ds_read_b128 v[220:223], v228 offset:18432
	ds_read_b128 v[224:227], v228 offset:19456
	s_mov_b32 m0, s69
	s_nop 0
	global_load_lds_dwordx4 v132, s[56:57]
	s_add_i32 m0, s69, 0x2000
	s_nop 0
	global_load_lds_dwordx4 v138, s[56:57]
	s_barrier
	s_waitcnt lgkmcnt(0)
	s_setprio 0
	v_mfma_f32_16x16x32_bf16 v[112:115], v[212:215], v[180:183], v[112:115]
	v_mfma_f32_16x16x32_bf16 v[108:111], v[220:223], v[180:183], v[108:111]
	v_mfma_f32_16x16x32_bf16 v[96:99], v[212:215], v[188:191], v[96:99]
	v_mfma_f32_16x16x32_bf16 v[92:95], v[220:223], v[188:191], v[92:95]
	v_mfma_f32_16x16x32_bf16 v[80:83], v[212:215], v[196:199], v[80:83]
	v_mfma_f32_16x16x32_bf16 v[76:79], v[220:223], v[196:199], v[76:79]
	v_mfma_f32_16x16x32_bf16 v[72:75], v[212:215], v[204:207], v[72:75]
	v_mfma_f32_16x16x32_bf16 v[68:71], v[220:223], v[204:207], v[68:71]
	v_mfma_f32_16x16x32_bf16 v[112:115], v[216:219], v[184:187], v[112:115]
	v_mfma_f32_16x16x32_bf16 v[108:111], v[224:227], v[184:187], v[108:111]
	v_mfma_f32_16x16x32_bf16 v[96:99], v[216:219], v[192:195], v[96:99]
	v_mfma_f32_16x16x32_bf16 v[92:95], v[224:227], v[192:195], v[92:95]
	v_mfma_f32_16x16x32_bf16 v[80:83], v[216:219], v[200:203], v[80:83]
	v_mfma_f32_16x16x32_bf16 v[76:79], v[224:227], v[200:203], v[76:79]
	s_setprio 3
	s_mov_b32 m0, s52
	s_barrier
	v_mfma_f32_16x16x32_bf16 v[72:75], v[216:219], v[208:211], v[72:75]
	v_mfma_f32_16x16x32_bf16 v[68:71], v[224:227], v[208:211], v[68:71]
	s_setprio 2
	ds_read_b128 v[180:183], v146 offset:16384
	ds_read_b128 v[184:187], v146 offset:17408
	ds_read_b128 v[188:191], v146 offset:18432
	ds_read_b128 v[192:195], v146 offset:19456
	ds_read_b128 v[196:199], v146 offset:20480
	ds_read_b128 v[200:203], v146 offset:21504
	ds_read_b128 v[204:207], v146 offset:22528
	ds_read_b128 v[208:211], v146 offset:23552
	global_load_lds_dwordx4 v132, s[4:5]
	s_mov_b32 m0, s53
	s_nop 0
	global_load_lds_dwordx4 v138, s[4:5]
	s_waitcnt vmcnt(10)
	s_barrier
	s_waitcnt lgkmcnt(0)
	s_setprio 0
	v_mfma_f32_16x16x32_bf16 v[64:67], v[148:151], v[180:183], v[64:67]
	v_mfma_f32_16x16x32_bf16 v[60:63], v[156:159], v[180:183], v[60:63]
	v_mfma_f32_16x16x32_bf16 v[56:59], v[148:151], v[188:191], v[56:59]
	v_mfma_f32_16x16x32_bf16 v[52:55], v[156:159], v[188:191], v[52:55]
	v_mfma_f32_16x16x32_bf16 v[40:43], v[148:151], v[196:199], v[40:43]
	v_mfma_f32_16x16x32_bf16 v[36:39], v[156:159], v[196:199], v[36:39]
	v_mfma_f32_16x16x32_bf16 v[24:27], v[148:151], v[204:207], v[24:27]
	v_mfma_f32_16x16x32_bf16 v[20:23], v[156:159], v[204:207], v[20:23]
	v_mfma_f32_16x16x32_bf16 v[64:67], v[152:155], v[184:187], v[64:67]
	v_mfma_f32_16x16x32_bf16 v[60:63], v[176:179], v[184:187], v[60:63]
	v_mfma_f32_16x16x32_bf16 v[56:59], v[152:155], v[192:195], v[56:59]
	v_mfma_f32_16x16x32_bf16 v[52:55], v[176:179], v[192:195], v[52:55]
	v_mfma_f32_16x16x32_bf16 v[40:43], v[152:155], v[200:203], v[40:43]
	v_mfma_f32_16x16x32_bf16 v[36:39], v[176:179], v[200:203], v[36:39]
	s_setprio 3
	s_barrier
	v_mfma_f32_16x16x32_bf16 v[24:27], v[152:155], v[208:211], v[24:27]
	v_mfma_f32_16x16x32_bf16 v[20:23], v[176:179], v[208:211], v[20:23]
	s_setprio 2
	ds_read_b128 v[148:151], v228 offset:32768
	ds_read_b128 v[152:155], v228 offset:33792
	ds_read_b128 v[156:159], v228 offset:34816
	ds_read_b128 v[176:179], v228 offset:35840
	s_add_u32 s70, s56, 0x4000
	s_addc_u32 s71, s57, 0
	s_add_i32 s69, s72, s39
	s_mov_b32 m0, s69
	s_nop 0
	global_load_lds_dwordx4 v132, s[70:71]
	s_add_i32 m0, s69, 0x2000
	s_nop 0
	global_load_lds_dwordx4 v138, s[70:71]
	s_waitcnt vmcnt(6)
	s_barrier
; #define PG8_STAGE(bufoff, gbase, voff) do { _Pragma("unroll") for (int _i = 0; _i < 2; ++_i) \
;         __builtin_amdgcn_global_load_lds((const unsigned*)((const char*)(gbase) + (voff)[_i]), (LAS unsigned*)(lds + (bufoff) + ldsw + _i * 8192), 16, 0, 0); } while (0)
; #define PG8_LDA(dst, b, h) do { _Pragma("unroll") for (int m = 0; m < 4; ++m) _Pragma("unroll") for (int k = 0; k < 2; ++k) dst[m][k] = *(const LAS bf16x8*)(lds + PG8_SA(b, h) + aoff + m * 2048 + k * 1024); } while (0)
; #define PG8_LDB(dst, b, h) do { _Pragma("unroll") for (int n = 0; n < 2; ++n) _Pragma("unroll") for (int k = 0; k < 2; ++k) dst[n][k] = *(const LAS bf16x8*)(lds + PG8_SB(b, h) + boff + n * 2048 + k * 1024); } while (0)
; #define PG8_MMA(ai, bj, At, Bt) do { __builtin_amdgcn_s_setprio(1); _Pragma("unroll") for (int m = 0; m < 4; ++m) _Pragma("unroll") for (int n = 0; n < 2; ++n) _Pragma("unroll") for (int k = 0; k < 2; ++k) \
;         acc[ai][bj][m][n] = __builtin_amdgcn_mfma_f32_16x16x32_bf16(Bt[n][k], At[m][k], acc[ai][bj][m][n], 0, 0, 0); __builtin_amdgcn_s_setprio(0); } while (0)
; #define PG8_WAIT_V(n) asm volatile("s_waitcnt vmcnt(" #n ")" ::: "memory")
; #define PG8_WAIT_L(n) asm volatile("s_waitcnt lgkmcnt(" #n ")" ::: "memory")
; #define PG8_BAR __builtin_amdgcn_s_barrier()
; #define PG8_SCHED __builtin_amdgcn_sched_barrier(0)
; template <class Epi, class Sched, int LD>
; __device__ __forceinline__ void gemm_phase(LAS unsigned char* lds, const Gemm g, const Sched& S, const Epi& E) {
;     ...
;             PG8_WAIT_V(6); PG8_BAR; PG8_MMA(1, 1, At, B1); PG8_BAR;
;             PG8_LDB(B0, 1, 0); PG8_SCHED; PG8_LDA(At, 1, 0); PG8_STAGE(PG8_SA(0, 1), a2 + hstep, voffA);
;             PG8_WAIT_L(8); PG8_BAR; PG8_WAIT_L(0); PG8_MMA(0, 0, At, B0); PG8_BAR; PG8_SCHED;
;             PG8_LDB(B1, 1, 1); PG8_STAGE(PG8_SB(1, 0), b3, voffB);
;             PG8_BAR; PG8_WAIT_L(0); PG8_MMA(0, 1, At, B1); PG8_BAR;
;             PG8_LDA(At, 1, 1); PG8_STAGE(PG8_SA(1, 0), a3, voffA);
;             PG8_BAR; PG8_WAIT_L(0); PG8_MMA(1, 0, At, B0); PG8_BAR; PG8_SCHED;
	s_setprio 0
	v_mfma_f32_16x16x32_bf16 v[48:51], v[212:215], v[180:183], v[48:51]
	v_mfma_f32_16x16x32_bf16 v[44:47], v[220:223], v[180:183], v[44:47]
	v_mfma_f32_16x16x32_bf16 v[32:35], v[212:215], v[188:191], v[32:35]
	v_mfma_f32_16x16x32_bf16 v[28:31], v[220:223], v[188:191], v[28:31]
	v_mfma_f32_16x16x32_bf16 v[16:19], v[212:215], v[196:199], v[16:19]
	v_mfma_f32_16x16x32_bf16 v[12:15], v[220:223], v[196:199], v[12:15]
	v_mfma_f32_16x16x32_bf16 v[8:11], v[212:215], v[204:207], v[8:11]
	v_mfma_f32_16x16x32_bf16 v[4:7], v[220:223], v[204:207], v[4:7]
	v_mfma_f32_16x16x32_bf16 v[48:51], v[216:219], v[184:187], v[48:51]
	v_mfma_f32_16x16x32_bf16 v[44:47], v[224:227], v[184:187], v[44:47]
	v_mfma_f32_16x16x32_bf16 v[32:35], v[216:219], v[192:195], v[32:35]
	v_mfma_f32_16x16x32_bf16 v[28:31], v[224:227], v[192:195], v[28:31]
	v_mfma_f32_16x16x32_bf16 v[16:19], v[216:219], v[200:203], v[16:19]
	v_mfma_f32_16x16x32_bf16 v[12:15], v[224:227], v[200:203], v[12:15]
	s_setprio 3
	s_add_i32 s69, 0, 0x18000
	s_barrier
	v_mfma_f32_16x16x32_bf16 v[8:11], v[216:219], v[208:211], v[8:11]
	v_mfma_f32_16x16x32_bf16 v[4:7], v[224:227], v[208:211], v[4:7]
	s_setprio 2
	s_add_u32 s4, s4, 0x4000
	s_addc_u32 s5, s5, 0
	s_mov_b32 m0, s60
	ds_read_b128 v[180:183], v146 offset:32768
	ds_read_b128 v[184:187], v146 offset:33792
	ds_read_b128 v[188:191], v146 offset:34816
	ds_read_b128 v[192:195], v146 offset:35840
	ds_read_b128 v[196:199], v146 offset:36864
	ds_read_b128 v[200:203], v146 offset:37888
	ds_read_b128 v[204:207], v146 offset:38912
	ds_read_b128 v[208:211], v146 offset:39936
	global_load_lds_dwordx4 v132, s[4:5]
	s_mov_b32 m0, s61
	s_nop 0
	global_load_lds_dwordx4 v138, s[4:5]
	s_waitcnt lgkmcnt(8)
	s_barrier
	s_waitcnt lgkmcnt(0)
	s_setprio 0
	v_mfma_f32_16x16x32_bf16 v[128:131], v[148:151], v[180:183], v[128:131]
	v_mfma_f32_16x16x32_bf16 v[124:127], v[156:159], v[180:183], v[124:127]
	v_mfma_f32_16x16x32_bf16 v[120:123], v[148:151], v[188:191], v[120:123]
	v_mfma_f32_16x16x32_bf16 v[116:119], v[156:159], v[188:191], v[116:119]
	v_mfma_f32_16x16x32_bf16 v[104:107], v[148:151], v[196:199], v[104:107]
	v_mfma_f32_16x16x32_bf16 v[100:103], v[156:159], v[196:199], v[100:103]
	v_mfma_f32_16x16x32_bf16 v[88:91], v[148:151], v[204:207], v[88:91]
	v_mfma_f32_16x16x32_bf16 v[84:87], v[156:159], v[204:207], v[84:87]
	v_mfma_f32_16x16x32_bf16 v[128:131], v[152:155], v[184:187], v[128:131]
	v_mfma_f32_16x16x32_bf16 v[124:127], v[176:179], v[184:187], v[124:127]
	v_mfma_f32_16x16x32_bf16 v[120:123], v[152:155], v[192:195], v[120:123]
	v_mfma_f32_16x16x32_bf16 v[116:119], v[176:179], v[192:195], v[116:119]
	v_mfma_f32_16x16x32_bf16 v[104:107], v[152:155], v[200:203], v[104:107]
	v_mfma_f32_16x16x32_bf16 v[100:103], v[176:179], v[200:203], v[100:103]
	s_setprio 3
	s_barrier
	v_mfma_f32_16x16x32_bf16 v[88:91], v[152:155], v[208:211], v[88:91]
	v_mfma_f32_16x16x32_bf16 v[84:87], v[176:179], v[208:211], v[84:87]
	s_setprio 2
	s_add_i32 s70, 0, 0x1c000
	s_add_u32 s4, s56, 0x8000
	s_addc_u32 s5, s57, 0
	s_add_i32 s69, s69, s39
	ds_read_b128 v[212:215], v228 offset:49152
	ds_read_b128 v[216:219], v228 offset:50176
	ds_read_b128 v[220:223], v228 offset:51200
	ds_read_b128 v[224:227], v228 offset:52224
	s_mov_b32 m0, s69
	s_nop 0
	global_load_lds_dwordx4 v132, s[4:5]
	s_add_i32 m0, s69, 0x2000
	s_nop 0
	global_load_lds_dwordx4 v138, s[4:5]
	s_barrier
	s_waitcnt lgkmcnt(0)
	s_setprio 0
	v_mfma_f32_16x16x32_bf16 v[112:115], v[212:215], v[180:183], v[112:115]
	v_mfma_f32_16x16x32_bf16 v[108:111], v[220:223], v[180:183], v[108:111]
	v_mfma_f32_16x16x32_bf16 v[96:99], v[212:215], v[188:191], v[96:99]
	v_mfma_f32_16x16x32_bf16 v[92:95], v[220:223], v[188:191], v[92:95]
	v_mfma_f32_16x16x32_bf16 v[80:83], v[212:215], v[196:199], v[80:83]
	v_mfma_f32_16x16x32_bf16 v[76:79], v[220:223], v[196:199], v[76:79]
	v_mfma_f32_16x16x32_bf16 v[72:75], v[212:215], v[204:207], v[72:75]
	v_mfma_f32_16x16x32_bf16 v[68:71], v[220:223], v[204:207], v[68:71]
	v_mfma_f32_16x16x32_bf16 v[112:115], v[216:219], v[184:187], v[112:115]
	v_mfma_f32_16x16x32_bf16 v[108:111], v[224:227], v[184:187], v[108:111]
	v_mfma_f32_16x16x32_bf16 v[96:99], v[216:219], v[192:195], v[96:99]
	v_mfma_f32_16x16x32_bf16 v[92:95], v[224:227], v[192:195], v[92:95]
	v_mfma_f32_16x16x32_bf16 v[80:83], v[216:219], v[200:203], v[80:83]
	v_mfma_f32_16x16x32_bf16 v[76:79], v[224:227], v[200:203], v[76:79]
	s_setprio 3
	s_mov_b32 m0, s64
	s_barrier
	v_mfma_f32_16x16x32_bf16 v[72:75], v[216:219], v[208:211], v[72:75]
	v_mfma_f32_16x16x32_bf16 v[68:71], v[224:227], v[208:211], v[68:71]
	s_setprio 2
	ds_read_b128 v[180:183], v146 offset:49152
	ds_read_b128 v[184:187], v146 offset:50176
	ds_read_b128 v[188:191], v146 offset:51200
	ds_read_b128 v[192:195], v146 offset:52224
	ds_read_b128 v[196:199], v146 offset:53248
	ds_read_b128 v[200:203], v146 offset:54272
	ds_read_b128 v[204:207], v146 offset:55296
	ds_read_b128 v[208:211], v146 offset:56320
	global_load_lds_dwordx4 v132, s[58:59]
	s_mov_b32 m0, s65
	s_nop 0
	global_load_lds_dwordx4 v138, s[58:59]
	s_waitcnt vmcnt(10)
	s_barrier
; #define PG8_STAGE(bufoff, gbase, voff) do { _Pragma("unroll") for (int _i = 0; _i < 2; ++_i) \
;         __builtin_amdgcn_global_load_lds((const unsigned*)((const char*)(gbase) + (voff)[_i]), (LAS unsigned*)(lds + (bufoff) + ldsw + _i * 8192), 16, 0, 0); } while (0)
; #define PG8_MMA(ai, bj, At, Bt) do { __builtin_amdgcn_s_setprio(1); _Pragma("unroll") for (int m = 0; m < 4; ++m) _Pragma("unroll") for (int n = 0; n < 2; ++n) _Pragma("unroll") for (int k = 0; k < 2; ++k) \
;         acc[ai][bj][m][n] = __builtin_amdgcn_mfma_f32_16x16x32_bf16(Bt[n][k], At[m][k], acc[ai][bj][m][n], 0, 0, 0); __builtin_amdgcn_s_setprio(0); } while (0)
; #define PG8_WAIT_V(n) asm volatile("s_waitcnt vmcnt(" #n ")" ::: "memory")
; #define PG8_WAIT_L(n) asm volatile("s_waitcnt lgkmcnt(" #n ")" ::: "memory")
; #define PG8_BAR __builtin_amdgcn_s_barrier()
; #define PG8_SCHED __builtin_amdgcn_sched_barrier(0)
;     __device__ __forceinline__ void operator()(const f32x4 (&acc)[2][2][4][2], const Unit& u, int wr, int wc, int fr, int fq) const {
;     ...
;         } else if (wc == 0) {
; #pragma unroll
;             for (int ai = 0; ai < 2; ++ai)
; #pragma unroll
;                 for (int m = 0; m < 4; ++m) {
;                     float* rowp = DT + (size_t)(row0 + ai * HALF + m * 16) * 32 + 8 * fq;
;                     *(f32x4*)rowp = acc[ai][0][m][0]; *(f32x4*)(rowp + 4) = acc[ai][0][m][1];
;                 }
;         }
; template <class Epi, class Sched, int LD>
; __device__ __forceinline__ void gemm_phase(LAS unsigned char* lds, const Gemm g, const Sched& S, const Epi& E) {
;     ...
;             PG8_BAR; PG8_WAIT_L(0); PG8_MMA(1, 0, At, B0); PG8_BAR; PG8_SCHED;
;             PG8_STAGE(PG8_SB(1, 1), b3 + hstep, voffB);
;             PG8_WAIT_V(6); PG8_BAR; PG8_MMA(1, 1, At, B1); PG8_BAR;
	s_waitcnt lgkmcnt(0)
	s_setprio 0
	v_mfma_f32_16x16x32_bf16 v[64:67], v[148:151], v[180:183], v[64:67]
	v_mfma_f32_16x16x32_bf16 v[60:63], v[156:159], v[180:183], v[60:63]
	v_mfma_f32_16x16x32_bf16 v[56:59], v[148:151], v[188:191], v[56:59]
	v_mfma_f32_16x16x32_bf16 v[52:55], v[156:159], v[188:191], v[52:55]
	v_mfma_f32_16x16x32_bf16 v[40:43], v[148:151], v[196:199], v[40:43]
	v_mfma_f32_16x16x32_bf16 v[36:39], v[156:159], v[196:199], v[36:39]
	v_mfma_f32_16x16x32_bf16 v[24:27], v[148:151], v[204:207], v[24:27]
	v_mfma_f32_16x16x32_bf16 v[20:23], v[156:159], v[204:207], v[20:23]
	v_mfma_f32_16x16x32_bf16 v[64:67], v[152:155], v[184:187], v[64:67]
	v_mfma_f32_16x16x32_bf16 v[60:63], v[176:179], v[184:187], v[60:63]
	v_mfma_f32_16x16x32_bf16 v[56:59], v[152:155], v[192:195], v[56:59]
	v_mfma_f32_16x16x32_bf16 v[52:55], v[176:179], v[192:195], v[52:55]
	v_mfma_f32_16x16x32_bf16 v[40:43], v[152:155], v[200:203], v[40:43]
	v_mfma_f32_16x16x32_bf16 v[36:39], v[176:179], v[200:203], v[36:39]
	s_setprio 3
	s_barrier
	v_mfma_f32_16x16x32_bf16 v[24:27], v[152:155], v[208:211], v[24:27]
	v_mfma_f32_16x16x32_bf16 v[20:23], v[176:179], v[208:211], v[20:23]
	s_setprio 2
	ds_read_b128 v[148:151], v228
	ds_read_b128 v[152:155], v228 offset:1024
	ds_read_b128 v[156:159], v228 offset:2048
	ds_read_b128 v[176:179], v228 offset:3072
	s_add_u32 s4, s56, 0xc000
	s_addc_u32 s5, s57, 0
	s_add_i32 s56, s70, s39
	s_mov_b32 m0, s56
	s_nop 0
	global_load_lds_dwordx4 v132, s[4:5]
	s_add_i32 m0, s56, 0x2000
	s_nop 0
	global_load_lds_dwordx4 v138, s[4:5]
	s_waitcnt vmcnt(6)
	s_barrier
	s_setprio 0
	v_mfma_f32_16x16x32_bf16 v[48:51], v[212:215], v[180:183], v[48:51]
	v_mfma_f32_16x16x32_bf16 v[44:47], v[220:223], v[180:183], v[44:47]
	v_mfma_f32_16x16x32_bf16 v[32:35], v[212:215], v[188:191], v[32:35]
	v_mfma_f32_16x16x32_bf16 v[28:31], v[220:223], v[188:191], v[28:31]
	v_mfma_f32_16x16x32_bf16 v[16:19], v[212:215], v[196:199], v[16:19]
	v_mfma_f32_16x16x32_bf16 v[12:15], v[220:223], v[196:199], v[12:15]
	v_mfma_f32_16x16x32_bf16 v[8:11], v[212:215], v[204:207], v[8:11]
	v_mfma_f32_16x16x32_bf16 v[4:7], v[220:223], v[204:207], v[4:7]
	v_mfma_f32_16x16x32_bf16 v[48:51], v[216:219], v[184:187], v[48:51]
	v_mfma_f32_16x16x32_bf16 v[44:47], v[224:227], v[184:187], v[44:47]
	v_mfma_f32_16x16x32_bf16 v[32:35], v[216:219], v[192:195], v[32:35]
	v_mfma_f32_16x16x32_bf16 v[28:31], v[224:227], v[192:195], v[28:31]
	v_mfma_f32_16x16x32_bf16 v[16:19], v[216:219], v[200:203], v[16:19]
	v_mfma_f32_16x16x32_bf16 v[12:15], v[224:227], v[200:203], v[12:15]
	s_setprio 3
	s_add_i32 s49, s49, 2
	s_add_u32 s54, s54, 0x10000
	s_addc_u32 s55, s55, 0
	s_add_u32 s29, s29, 0x10000
	s_addc_u32 s47, s47, 0
	s_cmp_gt_u32 s49, 29
	s_barrier
	v_mfma_f32_16x16x32_bf16 v[8:11], v[216:219], v[208:211], v[8:11]
	v_mfma_f32_16x16x32_bf16 v[4:7], v[224:227], v[208:211], v[4:7]
	s_setprio 2
	s_cbranch_scc0 .LBB0_501
	s_setprio 0
	v_lshl_add_u32 v142, s68, 8, v137
	s_cmp_gt_i32 s67, 35
	s_mov_b64 s[4:5], -1
	s_cbranch_scc0 .LBB0_506
	s_andn2_b64 vcc, exec, s[42:43]
	s_cbranch_vccnz .LBB0_505
	v_or_b32_e32 v150, 16, v142
	v_ashrrev_i32_e32 v143, 31, v142
	v_ashrrev_i32_e32 v151, 31, v150
	v_lshlrev_b64 v[148:149], 7, v[142:143]
	v_lshlrev_b64 v[150:151], 7, v[150:151]
	v_lshl_add_u64 v[148:149], v[140:141], 0, v[148:149]
	v_lshl_add_u64 v[150:151], v[140:141], 0, v[150:151]
	global_store_dwordx4 v[148:149], v[128:131], off
	global_store_dwordx4 v[148:149], v[124:127], off offset:16
	global_store_dwordx4 v[150:151], v[120:123], off
	global_store_dwordx4 v[150:151], v[116:119], off offset:16
	v_or_b32_e32 v150, 32, v142
	v_ashrrev_i32_e32 v151, 31, v150
	v_lshlrev_b64 v[150:151], 7, v[150:151]
	v_lshl_add_u64 v[150:151], v[140:141], 0, v[150:151]
	global_store_dwordx4 v[150:151], v[104:107], off
	global_store_dwordx4 v[150:151], v[100:103], off offset:16
	v_or_b32_e32 v150, 48, v142
	v_ashrrev_i32_e32 v151, 31, v150
	v_lshlrev_b64 v[150:151], 7, v[150:151]
	v_lshl_add_u64 v[150:151], v[140:141], 0, v[150:151]
	s_mov_b64 s[4:5], 0x4000
	global_store_dwordx4 v[150:151], v[88:91], off
	global_store_dwordx4 v[150:151], v[84:87], off offset:16
	v_lshl_add_u64 v[150:151], v[148:149], 0, s[4:5]
	s_movk_i32 s4, 0x4000
	v_add_co_u32_e32 v152, vcc, s4, v148
	s_mov_b64 s[4:5], 0x4800
	s_nop 0
	v_addc_co_u32_e32 v153, vcc, 0, v149, vcc
	global_store_dwordx4 v[152:153], v[64:67], off
	global_store_dwordx4 v[150:151], v[60:63], off offset:16
	v_lshl_add_u64 v[150:151], v[148:149], 0, s[4:5]
	global_store_dwordx4 v[152:153], v[56:59], off offset:2048
	global_store_dwordx4 v[150:151], v[52:55], off offset:16
	s_mov_b64 s[4:5], 0x5000
	v_add_co_u32_e32 v152, vcc, 0x5000, v148
	v_lshl_add_u64 v[150:151], v[148:149], 0, s[4:5]
	s_nop 0
	v_addc_co_u32_e32 v153, vcc, 0, v149, vcc
	s_mov_b64 s[4:5], 0x5800
	global_store_dwordx4 v[152:153], v[40:43], off
	global_store_dwordx4 v[150:151], v[36:39], off offset:16
	v_lshl_add_u64 v[148:149], v[148:149], 0, s[4:5]
	global_store_dwordx4 v[152:153], v[24:27], off offset:2048
	global_store_dwordx4 v[148:149], v[20:23], off offset:16

; #define PG8_STAGE(bufoff, gbase, voff) do { _Pragma("unroll") for (int _i = 0; _i < 2; ++_i) \
;         __builtin_amdgcn_global_load_lds((const unsigned*)((const char*)(gbase) + (voff)[_i]), (LAS unsigned*)(lds + (bufoff) + ldsw + _i * 8192), 16, 0, 0); } while (0)
; #define PG8_LDA(dst, b, h) do { _Pragma("unroll") for (int m = 0; m < 4; ++m) _Pragma("unroll") for (int k = 0; k < 2; ++k) dst[m][k] = *(const LAS bf16x8*)(lds + PG8_SA(b, h) + aoff + m * 2048 + k * 1024); } while (0)
; #define PG8_LDB(dst, b, h) do { _Pragma("unroll") for (int n = 0; n < 2; ++n) _Pragma("unroll") for (int k = 0; k < 2; ++k) dst[n][k] = *(const LAS bf16x8*)(lds + PG8_SB(b, h) + boff + n * 2048 + k * 1024); } while (0)
; #define PG8_MMA(ai, bj, At, Bt) do { __builtin_amdgcn_s_setprio(1); _Pragma("unroll") for (int m = 0; m < 4; ++m) _Pragma("unroll") for (int n = 0; n < 2; ++n) _Pragma("unroll") for (int k = 0; k < 2; ++k) \
;         acc[ai][bj][m][n] = __builtin_amdgcn_mfma_f32_16x16x32_bf16(Bt[n][k], At[m][k], acc[ai][bj][m][n], 0, 0, 0); __builtin_amdgcn_s_setprio(0); } while (0)
; #define PG8_WAIT_V(n) asm volatile("s_waitcnt vmcnt(" #n ")" ::: "memory")
; #define PG8_WAIT_L(n) asm volatile("s_waitcnt lgkmcnt(" #n ")" ::: "memory")
; template <class Epi, class Sched, int LD>
; __device__ __forceinline__ void gemm_phase(LAS unsigned char* lds, const Gemm g, const Sched& S, const Epi& E) {
;     ...
;         for (int t = 0; t < nt; t += 2) {
;             const bool last = (t == nt - 2);
;             const char* a1 = cA + (size_t)(t + 1) * kstep;
;             const char* a2 = last ? nA : cA + (size_t)(t + 2) * kstep; const char* b2 = last ? nB : cB + (size_t)(t + 2) * kstep;
;             const char* a3 = a2 + kstep; const char* b3 = b2 + kstep;
;             PG8_LDB(B0, 0, 0); PG8_SCHED; PG8_LDA(At, 0, 0); PG8_STAGE(PG8_SA(1, 1), a1 + hstep, voffA);
;             PG8_WAIT_L(8); PG8_BAR; PG8_WAIT_L(0); PG8_MMA(0, 0, At, B0); PG8_BAR; PG8_SCHED;
;             PG8_LDB(B1, 0, 1); PG8_STAGE(PG8_SB(0, 0), b2, voffB);
;             PG8_BAR; PG8_WAIT_L(0); PG8_MMA(0, 1, At, B1); PG8_BAR;
;             PG8_LDA(At, 0, 1); PG8_STAGE(PG8_SA(0, 0), a2, voffA);
;             PG8_BAR; PG8_WAIT_L(0); PG8_MMA(1, 0, At, B0); PG8_BAR; PG8_SCHED;
;             PG8_STAGE(PG8_SB(0, 1), b2 + hstep, voffB);
;             PG8_WAIT_V(6); PG8_BAR; PG8_MMA(1, 1, At, B1); PG8_BAR;
.LBB0_899:
	s_add_u32 s4, s50, 0x4000
	s_addc_u32 s5, s51, 0
	s_cmp_eq_u32 s70, 28
	s_cselect_b32 s4, s48, s4
	s_cselect_b32 s5, s49, s5
	s_cselect_b32 s54, s40, s45
	s_cselect_b32 s55, s41, s47
	s_add_u32 s56, s4, 0x8000
	s_addc_u32 s57, s5, 0
	s_add_i32 s71, 0, 0x10000
	s_add_i32 m0, s29, 0xc000
	ds_read_b128 v[180:183], v144
	ds_read_b128 v[184:187], v144 offset:1024
	ds_read_b128 v[188:191], v144 offset:2048
	ds_read_b128 v[192:195], v144 offset:3072
	ds_read_b128 v[196:199], v144 offset:4096
	ds_read_b128 v[200:203], v144 offset:5120
	ds_read_b128 v[204:207], v144 offset:6144
	ds_read_b128 v[208:211], v144 offset:7168
	global_load_lds_dwordx4 v138, s[50:51]
	s_add_i32 m0, s29, 0xe000
	s_nop 0
	global_load_lds_dwordx4 v140, s[50:51]
	s_waitcnt lgkmcnt(8)
	s_barrier
	s_waitcnt lgkmcnt(0)
	s_setprio 0
	v_mfma_f32_16x16x32_bf16 v[128:131], v[146:149], v[180:183], v[128:131]
	v_mfma_f32_16x16x32_bf16 v[120:123], v[154:157], v[180:183], v[120:123]
	v_mfma_f32_16x16x32_bf16 v[112:115], v[146:149], v[188:191], v[112:115]
	v_mfma_f32_16x16x32_bf16 v[104:107], v[154:157], v[188:191], v[104:107]
	v_mfma_f32_16x16x32_bf16 v[96:99], v[146:149], v[196:199], v[96:99]
	v_mfma_f32_16x16x32_bf16 v[88:91], v[154:157], v[196:199], v[88:91]
	v_mfma_f32_16x16x32_bf16 v[80:83], v[146:149], v[204:207], v[80:83]
	v_mfma_f32_16x16x32_bf16 v[72:75], v[154:157], v[204:207], v[72:75]
	v_mfma_f32_16x16x32_bf16 v[128:131], v[150:153], v[184:187], v[128:131]
	v_mfma_f32_16x16x32_bf16 v[120:123], v[176:179], v[184:187], v[120:123]
	v_mfma_f32_16x16x32_bf16 v[112:115], v[150:153], v[192:195], v[112:115]
	v_mfma_f32_16x16x32_bf16 v[104:107], v[176:179], v[192:195], v[104:107]
	v_mfma_f32_16x16x32_bf16 v[96:99], v[150:153], v[200:203], v[96:99]
	v_mfma_f32_16x16x32_bf16 v[88:91], v[176:179], v[200:203], v[88:91]
	s_setprio 3
	s_barrier
	v_mfma_f32_16x16x32_bf16 v[80:83], v[150:153], v[208:211], v[80:83]
	v_mfma_f32_16x16x32_bf16 v[72:75], v[176:179], v[208:211], v[72:75]
	s_setprio 2
	s_add_i32 s74, 0, 0x14000
	s_add_i32 s71, s71, s28
	s_mov_b32 m0, s71
	ds_read_b128 v[212:215], v228 offset:16384
	ds_read_b128 v[216:219], v228 offset:17408
	ds_read_b128 v[220:223], v228 offset:18432
	ds_read_b128 v[224:227], v228 offset:19456
	global_load_lds_dwordx4 v138, s[54:55]
	s_add_i32 m0, s71, 0x2000
	s_nop 0
	global_load_lds_dwordx4 v140, s[54:55]
	s_barrier
	s_waitcnt lgkmcnt(0)
	s_setprio 0
	v_mfma_f32_16x16x32_bf16 v[124:127], v[212:215], v[180:183], v[124:127]
	v_mfma_f32_16x16x32_bf16 v[116:119], v[220:223], v[180:183], v[116:119]
	v_mfma_f32_16x16x32_bf16 v[108:111], v[212:215], v[188:191], v[108:111]
	v_mfma_f32_16x16x32_bf16 v[100:103], v[220:223], v[188:191], v[100:103]
	v_mfma_f32_16x16x32_bf16 v[92:95], v[212:215], v[196:199], v[92:95]
	v_mfma_f32_16x16x32_bf16 v[84:87], v[220:223], v[196:199], v[84:87]
	v_mfma_f32_16x16x32_bf16 v[76:79], v[212:215], v[204:207], v[76:79]
	v_mfma_f32_16x16x32_bf16 v[68:71], v[220:223], v[204:207], v[68:71]
	v_mfma_f32_16x16x32_bf16 v[124:127], v[216:219], v[184:187], v[124:127]
	v_mfma_f32_16x16x32_bf16 v[116:119], v[224:227], v[184:187], v[116:119]
	v_mfma_f32_16x16x32_bf16 v[108:111], v[216:219], v[192:195], v[108:111]
	v_mfma_f32_16x16x32_bf16 v[100:103], v[224:227], v[192:195], v[100:103]
	v_mfma_f32_16x16x32_bf16 v[92:95], v[216:219], v[200:203], v[92:95]
	v_mfma_f32_16x16x32_bf16 v[84:87], v[224:227], v[200:203], v[84:87]
	s_setprio 3
	s_mov_b32 m0, s29
	s_barrier
	v_mfma_f32_16x16x32_bf16 v[76:79], v[216:219], v[208:211], v[76:79]
	v_mfma_f32_16x16x32_bf16 v[68:71], v[224:227], v[208:211], v[68:71]
	s_setprio 2
	ds_read_b128 v[180:183], v144 offset:16384
	ds_read_b128 v[184:187], v144 offset:17408
	ds_read_b128 v[188:191], v144 offset:18432
	ds_read_b128 v[192:195], v144 offset:19456
	ds_read_b128 v[196:199], v144 offset:20480
	ds_read_b128 v[200:203], v144 offset:21504
	ds_read_b128 v[204:207], v144 offset:22528
	ds_read_b128 v[208:211], v144 offset:23552
	global_load_lds_dwordx4 v138, s[4:5]
	s_mov_b32 m0, s39
	s_nop 0
	global_load_lds_dwordx4 v140, s[4:5]
	s_waitcnt vmcnt(10)
	s_barrier
	s_waitcnt lgkmcnt(0)
	s_setprio 0
	v_mfma_f32_16x16x32_bf16 v[64:67], v[146:149], v[180:183], v[64:67]
	v_mfma_f32_16x16x32_bf16 v[56:59], v[154:157], v[180:183], v[56:59]
	v_mfma_f32_16x16x32_bf16 v[48:51], v[146:149], v[188:191], v[48:51]
	v_mfma_f32_16x16x32_bf16 v[40:43], v[154:157], v[188:191], v[40:43]
	v_mfma_f32_16x16x32_bf16 v[32:35], v[146:149], v[196:199], v[32:35]
	v_mfma_f32_16x16x32_bf16 v[24:27], v[154:157], v[196:199], v[24:27]
	v_mfma_f32_16x16x32_bf16 v[16:19], v[146:149], v[204:207], v[16:19]
	v_mfma_f32_16x16x32_bf16 v[8:11], v[154:157], v[204:207], v[8:11]
	v_mfma_f32_16x16x32_bf16 v[64:67], v[150:153], v[184:187], v[64:67]
	v_mfma_f32_16x16x32_bf16 v[56:59], v[176:179], v[184:187], v[56:59]
	v_mfma_f32_16x16x32_bf16 v[48:51], v[150:153], v[192:195], v[48:51]
	v_mfma_f32_16x16x32_bf16 v[40:43], v[176:179], v[192:195], v[40:43]
	v_mfma_f32_16x16x32_bf16 v[32:35], v[150:153], v[200:203], v[32:35]
	v_mfma_f32_16x16x32_bf16 v[24:27], v[176:179], v[200:203], v[24:27]
	s_setprio 3
	s_barrier
	v_mfma_f32_16x16x32_bf16 v[16:19], v[150:153], v[208:211], v[16:19]
	v_mfma_f32_16x16x32_bf16 v[8:11], v[176:179], v[208:211], v[8:11]
	s_setprio 2
	ds_read_b128 v[146:149], v228 offset:32768
	ds_read_b128 v[150:153], v228 offset:33792
	ds_read_b128 v[154:157], v228 offset:34816
	ds_read_b128 v[176:179], v228 offset:35840
	s_add_u32 s72, s54, 0x4000
	s_addc_u32 s73, s55, 0
	s_add_i32 s71, s74, s28
	s_mov_b32 m0, s71
	s_nop 0
	global_load_lds_dwordx4 v138, s[72:73]
	s_add_i32 m0, s71, 0x2000
	s_nop 0
	global_load_lds_dwordx4 v140, s[72:73]
	s_waitcnt vmcnt(6)
	s_barrier
; #define PG8_STAGE(bufoff, gbase, voff) do { _Pragma("unroll") for (int _i = 0; _i < 2; ++_i) \
;         __builtin_amdgcn_global_load_lds((const unsigned*)((const char*)(gbase) + (voff)[_i]), (LAS unsigned*)(lds + (bufoff) + ldsw + _i * 8192), 16, 0, 0); } while (0)
; #define PG8_LDA(dst, b, h) do { _Pragma("unroll") for (int m = 0; m < 4; ++m) _Pragma("unroll") for (int k = 0; k < 2; ++k) dst[m][k] = *(const LAS bf16x8*)(lds + PG8_SA(b, h) + aoff + m * 2048 + k * 1024); } while (0)
; #define PG8_LDB(dst, b, h) do { _Pragma("unroll") for (int n = 0; n < 2; ++n) _Pragma("unroll") for (int k = 0; k < 2; ++k) dst[n][k] = *(const LAS bf16x8*)(lds + PG8_SB(b, h) + boff + n * 2048 + k * 1024); } while (0)
; #define PG8_MMA(ai, bj, At, Bt) do { __builtin_amdgcn_s_setprio(1); _Pragma("unroll") for (int m = 0; m < 4; ++m) _Pragma("unroll") for (int n = 0; n < 2; ++n) _Pragma("unroll") for (int k = 0; k < 2; ++k) \
;         acc[ai][bj][m][n] = __builtin_amdgcn_mfma_f32_16x16x32_bf16(Bt[n][k], At[m][k], acc[ai][bj][m][n], 0, 0, 0); __builtin_amdgcn_s_setprio(0); } while (0)
; #define PG8_WAIT_V(n) asm volatile("s_waitcnt vmcnt(" #n ")" ::: "memory")
; #define PG8_WAIT_L(n) asm volatile("s_waitcnt lgkmcnt(" #n ")" ::: "memory")
; #define PG8_BAR __builtin_amdgcn_s_barrier()
; #define PG8_SCHED __builtin_amdgcn_sched_barrier(0)
; template <class Epi, class Sched, int LD>
; __device__ __forceinline__ void gemm_phase(LAS unsigned char* lds, const Gemm g, const Sched& S, const Epi& E) {
;     ...
;             PG8_WAIT_V(6); PG8_BAR; PG8_MMA(1, 1, At, B1); PG8_BAR;
;             PG8_LDB(B0, 1, 0); PG8_SCHED; PG8_LDA(At, 1, 0); PG8_STAGE(PG8_SA(0, 1), a2 + hstep, voffA);
;             PG8_WAIT_L(8); PG8_BAR; PG8_WAIT_L(0); PG8_MMA(0, 0, At, B0); PG8_BAR; PG8_SCHED;
;             PG8_LDB(B1, 1, 1); PG8_STAGE(PG8_SB(1, 0), b3, voffB);
;             PG8_BAR; PG8_WAIT_L(0); PG8_MMA(0, 1, At, B1); PG8_BAR;
;             PG8_LDA(At, 1, 1); PG8_STAGE(PG8_SA(1, 0), a3, voffA);
;             PG8_BAR; PG8_WAIT_L(0); PG8_MMA(1, 0, At, B0); PG8_BAR; PG8_SCHED;
	s_setprio 0
	v_mfma_f32_16x16x32_bf16 v[60:63], v[212:215], v[180:183], v[60:63]
	v_mfma_f32_16x16x32_bf16 v[52:55], v[220:223], v[180:183], v[52:55]
	v_mfma_f32_16x16x32_bf16 v[44:47], v[212:215], v[188:191], v[44:47]
	v_mfma_f32_16x16x32_bf16 v[36:39], v[220:223], v[188:191], v[36:39]
	v_mfma_f32_16x16x32_bf16 v[28:31], v[212:215], v[196:199], v[28:31]
	v_mfma_f32_16x16x32_bf16 v[20:23], v[220:223], v[196:199], v[20:23]
	v_mfma_f32_16x16x32_bf16 v[12:15], v[212:215], v[204:207], v[12:15]
	v_mfma_f32_16x16x32_bf16 v[4:7], v[220:223], v[204:207], v[4:7]
	v_mfma_f32_16x16x32_bf16 v[60:63], v[216:219], v[184:187], v[60:63]
	v_mfma_f32_16x16x32_bf16 v[52:55], v[224:227], v[184:187], v[52:55]
	v_mfma_f32_16x16x32_bf16 v[44:47], v[216:219], v[192:195], v[44:47]
	v_mfma_f32_16x16x32_bf16 v[36:39], v[224:227], v[192:195], v[36:39]
	v_mfma_f32_16x16x32_bf16 v[28:31], v[216:219], v[200:203], v[28:31]
	v_mfma_f32_16x16x32_bf16 v[20:23], v[224:227], v[200:203], v[20:23]
	s_setprio 3
	s_add_i32 s71, 0, 0x18000
	s_barrier
	v_mfma_f32_16x16x32_bf16 v[12:15], v[216:219], v[208:211], v[12:15]
	v_mfma_f32_16x16x32_bf16 v[4:7], v[224:227], v[208:211], v[4:7]
	s_setprio 2
	s_add_u32 s4, s4, 0x4000
	s_addc_u32 s5, s5, 0
	s_mov_b32 m0, s52
	ds_read_b128 v[180:183], v144 offset:32768
	ds_read_b128 v[184:187], v144 offset:33792
	ds_read_b128 v[188:191], v144 offset:34816
	ds_read_b128 v[192:195], v144 offset:35840
	ds_read_b128 v[196:199], v144 offset:36864
	ds_read_b128 v[200:203], v144 offset:37888
	ds_read_b128 v[204:207], v144 offset:38912
	ds_read_b128 v[208:211], v144 offset:39936
	global_load_lds_dwordx4 v138, s[4:5]
	s_mov_b32 m0, s53
	s_nop 0
	global_load_lds_dwordx4 v140, s[4:5]
	s_waitcnt lgkmcnt(8)
	s_barrier
	s_waitcnt lgkmcnt(0)
	s_setprio 0
	v_mfma_f32_16x16x32_bf16 v[128:131], v[146:149], v[180:183], v[128:131]
	v_mfma_f32_16x16x32_bf16 v[120:123], v[154:157], v[180:183], v[120:123]
	v_mfma_f32_16x16x32_bf16 v[112:115], v[146:149], v[188:191], v[112:115]
	v_mfma_f32_16x16x32_bf16 v[104:107], v[154:157], v[188:191], v[104:107]
	v_mfma_f32_16x16x32_bf16 v[96:99], v[146:149], v[196:199], v[96:99]
	v_mfma_f32_16x16x32_bf16 v[88:91], v[154:157], v[196:199], v[88:91]
	v_mfma_f32_16x16x32_bf16 v[80:83], v[146:149], v[204:207], v[80:83]
	v_mfma_f32_16x16x32_bf16 v[72:75], v[154:157], v[204:207], v[72:75]
	v_mfma_f32_16x16x32_bf16 v[128:131], v[150:153], v[184:187], v[128:131]
	v_mfma_f32_16x16x32_bf16 v[120:123], v[176:179], v[184:187], v[120:123]
	v_mfma_f32_16x16x32_bf16 v[112:115], v[150:153], v[192:195], v[112:115]
	v_mfma_f32_16x16x32_bf16 v[104:107], v[176:179], v[192:195], v[104:107]
	v_mfma_f32_16x16x32_bf16 v[96:99], v[150:153], v[200:203], v[96:99]
	v_mfma_f32_16x16x32_bf16 v[88:91], v[176:179], v[200:203], v[88:91]
	s_setprio 3
	s_barrier
	v_mfma_f32_16x16x32_bf16 v[80:83], v[150:153], v[208:211], v[80:83]
	v_mfma_f32_16x16x32_bf16 v[72:75], v[176:179], v[208:211], v[72:75]
	s_setprio 2
	s_add_i32 s72, 0, 0x1c000
	s_add_u32 s4, s54, 0x8000
	s_addc_u32 s5, s55, 0
	s_add_i32 s71, s71, s28
	s_mov_b32 m0, s71
	ds_read_b128 v[212:215], v228 offset:49152
	ds_read_b128 v[216:219], v228 offset:50176
	ds_read_b128 v[220:223], v228 offset:51200
	ds_read_b128 v[224:227], v228 offset:52224
	global_load_lds_dwordx4 v138, s[4:5]
	s_add_i32 m0, s71, 0x2000
	s_nop 0
	global_load_lds_dwordx4 v140, s[4:5]
	s_barrier
	s_waitcnt lgkmcnt(0)
	s_setprio 0
	v_mfma_f32_16x16x32_bf16 v[124:127], v[212:215], v[180:183], v[124:127]
	v_mfma_f32_16x16x32_bf16 v[116:119], v[220:223], v[180:183], v[116:119]
	v_mfma_f32_16x16x32_bf16 v[108:111], v[212:215], v[188:191], v[108:111]
	v_mfma_f32_16x16x32_bf16 v[100:103], v[220:223], v[188:191], v[100:103]
	v_mfma_f32_16x16x32_bf16 v[92:95], v[212:215], v[196:199], v[92:95]
	v_mfma_f32_16x16x32_bf16 v[84:87], v[220:223], v[196:199], v[84:87]
	v_mfma_f32_16x16x32_bf16 v[76:79], v[212:215], v[204:207], v[76:79]
	v_mfma_f32_16x16x32_bf16 v[68:71], v[220:223], v[204:207], v[68:71]
	v_mfma_f32_16x16x32_bf16 v[124:127], v[216:219], v[184:187], v[124:127]
	v_mfma_f32_16x16x32_bf16 v[116:119], v[224:227], v[184:187], v[116:119]
	v_mfma_f32_16x16x32_bf16 v[108:111], v[216:219], v[192:195], v[108:111]
	v_mfma_f32_16x16x32_bf16 v[100:103], v[224:227], v[192:195], v[100:103]
	v_mfma_f32_16x16x32_bf16 v[92:95], v[216:219], v[200:203], v[92:95]
	v_mfma_f32_16x16x32_bf16 v[84:87], v[224:227], v[200:203], v[84:87]
	s_setprio 3
	s_mov_b32 m0, s60
	s_barrier
	v_mfma_f32_16x16x32_bf16 v[76:79], v[216:219], v[208:211], v[76:79]
	v_mfma_f32_16x16x32_bf16 v[68:71], v[224:227], v[208:211], v[68:71]
	s_setprio 2
	ds_read_b128 v[180:183], v144 offset:49152
	ds_read_b128 v[184:187], v144 offset:50176
	ds_read_b128 v[188:191], v144 offset:51200
	ds_read_b128 v[192:195], v144 offset:52224
	ds_read_b128 v[196:199], v144 offset:53248
	ds_read_b128 v[200:203], v144 offset:54272
	ds_read_b128 v[204:207], v144 offset:55296
	ds_read_b128 v[208:211], v144 offset:56320
	global_load_lds_dwordx4 v138, s[56:57]
	s_mov_b32 m0, s61
	s_nop 0
	global_load_lds_dwordx4 v140, s[56:57]
	s_waitcnt vmcnt(10)
	s_barrier
	s_waitcnt lgkmcnt(0)
	s_setprio 0
	v_mfma_f32_16x16x32_bf16 v[64:67], v[146:149], v[180:183], v[64:67]
	v_mfma_f32_16x16x32_bf16 v[56:59], v[154:157], v[180:183], v[56:59]
	v_mfma_f32_16x16x32_bf16 v[48:51], v[146:149], v[188:191], v[48:51]
	v_mfma_f32_16x16x32_bf16 v[40:43], v[154:157], v[188:191], v[40:43]
	v_mfma_f32_16x16x32_bf16 v[32:35], v[146:149], v[196:199], v[32:35]
	v_mfma_f32_16x16x32_bf16 v[24:27], v[154:157], v[196:199], v[24:27]
	v_mfma_f32_16x16x32_bf16 v[16:19], v[146:149], v[204:207], v[16:19]
	v_mfma_f32_16x16x32_bf16 v[8:11], v[154:157], v[204:207], v[8:11]
	v_mfma_f32_16x16x32_bf16 v[64:67], v[150:153], v[184:187], v[64:67]
	v_mfma_f32_16x16x32_bf16 v[56:59], v[176:179], v[184:187], v[56:59]
	v_mfma_f32_16x16x32_bf16 v[48:51], v[150:153], v[192:195], v[48:51]
	v_mfma_f32_16x16x32_bf16 v[40:43], v[176:179], v[192:195], v[40:43]
	v_mfma_f32_16x16x32_bf16 v[32:35], v[150:153], v[200:203], v[32:35]
	v_mfma_f32_16x16x32_bf16 v[24:27], v[176:179], v[200:203], v[24:27]
	s_setprio 3
	s_barrier
; __device__ __forceinline__ unsigned cvt_pk_bf16(float lo, float hi) { f32x2 v = {lo, hi}; bf16x2v b = __builtin_convertvector(v, bf16x2v); return __builtin_bit_cast(unsigned, b); }
; __device__ __forceinline__ float silu_f(float x) { return x * __builtin_amdgcn_rcpf(1.f + __expf(-x)); }
; #define PG8_STAGE(bufoff, gbase, voff) do { _Pragma("unroll") for (int _i = 0; _i < 2; ++_i) \
;         __builtin_amdgcn_global_load_lds((const unsigned*)((const char*)(gbase) + (voff)[_i]), (LAS unsigned*)(lds + (bufoff) + ldsw + _i * 8192), 16, 0, 0); } while (0)
; #define PG8_MMA(ai, bj, At, Bt) do { __builtin_amdgcn_s_setprio(1); _Pragma("unroll") for (int m = 0; m < 4; ++m) _Pragma("unroll") for (int n = 0; n < 2; ++n) _Pragma("unroll") for (int k = 0; k < 2; ++k) \
;         acc[ai][bj][m][n] = __builtin_amdgcn_mfma_f32_16x16x32_bf16(Bt[n][k], At[m][k], acc[ai][bj][m][n], 0, 0, 0); __builtin_amdgcn_s_setprio(0); } while (0)
; #define PG8_WAIT_V(n) asm volatile("s_waitcnt vmcnt(" #n ")" ::: "memory")
; #define PG8_BAR __builtin_amdgcn_s_barrier()
;     __device__ __forceinline__ void operator()(const f32x4 (&acc)[2][2][4][2], const Unit& u, int wr, int wc, int fr, int fq) const {
;         const int row0 = u.pm * BM + wr * 64 + fr, col0 = u.pn * 128 + wc * 32 + 8 * fq;
; #pragma unroll
;         for (int ai = 0; ai < 2; ++ai)
; #pragma unroll
;             for (int m = 0; m < 4; ++m) {
;                 bf16_t* rowp = O + img_off(row0 + ai * HALF + m * 16, col0, D_FF / 64);
;                 const f32x4 g0 = acc[ai][0][m][0], g1 = acc[ai][0][m][1], u0 = acc[ai][1][m][0], u1 = acc[ai][1][m][1];
;                 u32x4 w;
;                 w.x = cvt_pk_bf16(silu_f(g0[0]) * u0[0], silu_f(g0[1]) * u0[1]); w.y = cvt_pk_bf16(silu_f(g0[2]) * u0[2], silu_f(g0[3]) * u0[3]);
;                 w.z = cvt_pk_bf16(silu_f(g1[0]) * u1[0], silu_f(g1[1]) * u1[1]); w.w = cvt_pk_bf16(silu_f(g1[2]) * u1[2], silu_f(g1[3]) * u1[3]);
;                 *(u32x4*)rowp = w;
; template <class Epi, class Sched, int LD>
; __device__ __forceinline__ void gemm_phase(LAS unsigned char* lds, const Gemm g, const Sched& S, const Epi& E) {
;     ...
;             PG8_BAR; PG8_WAIT_L(0); PG8_MMA(1, 0, At, B0); PG8_BAR; PG8_SCHED;
;             PG8_STAGE(PG8_SB(1, 1), b3 + hstep, voffB);
;             PG8_WAIT_V(6); PG8_BAR; PG8_MMA(1, 1, At, B1); PG8_BAR;
;         }
;         E(acc, cur, wr, wc, fr, fq);
	v_mfma_f32_16x16x32_bf16 v[16:19], v[150:153], v[208:211], v[16:19]
	v_mfma_f32_16x16x32_bf16 v[8:11], v[176:179], v[208:211], v[8:11]
	s_setprio 2
	ds_read_b128 v[146:149], v228
	ds_read_b128 v[150:153], v228 offset:1024
	ds_read_b128 v[154:157], v228 offset:2048
	ds_read_b128 v[176:179], v228 offset:3072
	s_add_u32 s4, s54, 0xc000
	s_addc_u32 s5, s55, 0
	s_add_i32 s54, s72, s28
	s_mov_b32 m0, s54
	s_nop 0
	global_load_lds_dwordx4 v138, s[4:5]
	s_add_i32 m0, s54, 0x2000
	s_nop 0
	global_load_lds_dwordx4 v140, s[4:5]
	s_waitcnt vmcnt(6)
	s_barrier
	s_setprio 0
	v_mfma_f32_16x16x32_bf16 v[60:63], v[212:215], v[180:183], v[60:63]
	v_mfma_f32_16x16x32_bf16 v[52:55], v[220:223], v[180:183], v[52:55]
	v_mfma_f32_16x16x32_bf16 v[44:47], v[212:215], v[188:191], v[44:47]
	v_mfma_f32_16x16x32_bf16 v[36:39], v[220:223], v[188:191], v[36:39]
	v_mfma_f32_16x16x32_bf16 v[28:31], v[212:215], v[196:199], v[28:31]
	v_mfma_f32_16x16x32_bf16 v[20:23], v[220:223], v[196:199], v[20:23]
	v_mfma_f32_16x16x32_bf16 v[12:15], v[212:215], v[204:207], v[12:15]
	v_mfma_f32_16x16x32_bf16 v[4:7], v[220:223], v[204:207], v[4:7]
	v_mfma_f32_16x16x32_bf16 v[60:63], v[216:219], v[184:187], v[60:63]
	v_mfma_f32_16x16x32_bf16 v[52:55], v[224:227], v[184:187], v[52:55]
	v_mfma_f32_16x16x32_bf16 v[44:47], v[216:219], v[192:195], v[44:47]
	v_mfma_f32_16x16x32_bf16 v[36:39], v[224:227], v[192:195], v[36:39]
	v_mfma_f32_16x16x32_bf16 v[28:31], v[216:219], v[200:203], v[28:31]
	v_mfma_f32_16x16x32_bf16 v[20:23], v[224:227], v[200:203], v[20:23]
	s_setprio 3
	s_add_i32 s70, s70, 2
	s_add_u32 s50, s50, 0x10000
	s_addc_u32 s51, s51, 0
	s_add_u32 s45, s45, 0x10000
	s_addc_u32 s47, s47, 0
	s_cmp_gt_u32 s70, 29
	s_barrier
	v_mfma_f32_16x16x32_bf16 v[12:15], v[216:219], v[208:211], v[12:15]
	v_mfma_f32_16x16x32_bf16 v[4:7], v[224:227], v[208:211], v[4:7]
	s_setprio 2
	s_cbranch_scc0 .LBB0_899
	s_setprio 0
	v_mul_f32_e32 v148, 0xbfb8aa3b, v128
	v_mul_f32_e32 v149, 0xbfb8aa3b, v129
	v_exp_f32_e32 v148, v148
	v_exp_f32_e32 v149, v149
	s_lshl_b32 s5, s69, 8
	s_add_i32 s5, s5, s58
	v_add_f32_e32 v148, 1.0, v148
	v_add_f32_e32 v149, 1.0, v149
	v_rcp_f32_e32 v148, v148
	v_rcp_f32_e32 v149, v149
	s_lshl_b32 s4, s68, 7
	s_or_b32 s4, s4, s59
	s_ashr_i32 s45, s5, 8
	v_pk_mul_f32 v[128:129], v[128:129], v[148:149]
	s_ashr_i32 s4, s4, 6
	v_pk_mul_f32 v[124:125], v[128:129], v[124:125]
	s_mulk_i32 s45, 0x58
	v_cvt_pk_bf16_f32 v124, v124, v125
	v_mul_f32_e32 v125, 0xbfb8aa3b, v130
	v_exp_f32_e32 v125, v125
	s_add_i32 s50, s45, s4
	s_ashr_i32 s51, s50, 31
	s_lshl_b64 s[50:51], s[50:51], 15
	v_add_f32_e32 v125, 1.0, v125
	v_rcp_f32_e32 v128, v125
	v_mul_f32_e32 v125, 0xbfb8aa3b, v131
	v_exp_f32_e32 v125, v125
	s_add_u32 s45, s16, s50
	s_addc_u32 s47, s17, s51
	s_lshl_b32 s50, s5, 7
	v_add_f32_e32 v125, 1.0, v125
	v_rcp_f32_e32 v129, v125
	s_and_b32 s50, s50, 0x4000
	s_add_u32 s50, s45, s50
	s_addc_u32 s51, s47, 0
	v_pk_mul_f32 v[128:129], v[130:131], v[128:129]
	s_or_b32 s45, s5, 16
	v_pk_mul_f32 v[126:127], v[128:129], v[126:127]
	s_lshr_b32 s45, s45, 3
	v_cvt_pk_bf16_f32 v125, v126, v127
	v_mul_f32_e32 v126, 0xbfb8aa3b, v120
	v_mul_f32_e32 v127, 0xbfb8aa3b, v121
	v_exp_f32_e32 v126, v126
	v_exp_f32_e32 v127, v127
	v_or_b32_e32 v145, s5, v137
	s_and_b32 s45, s45, 10
	v_add_f32_e32 v126, 1.0, v126
	v_add_f32_e32 v127, 1.0, v127
	v_rcp_f32_e32 v126, v126
	v_rcp_f32_e32 v127, v127
	v_lshlrev_b32_e32 v132, 6, v145
	v_lshlrev_b32_e32 v146, 2, v145
	s_or_b32 s45, s45, s64
	v_pk_mul_f32 v[120:121], v[120:121], v[126:127]
	v_and_or_b32 v132, v132, s15, v142
	v_pk_mul_f32 v[116:117], v[120:121], v[116:117]
	v_and_b32_e32 v146, 32, v146
	v_cvt_pk_bf16_f32 v126, v116, v117
	v_mul_f32_e32 v116, 0xbfb8aa3b, v122
	v_mul_f32_e32 v117, 0xbfb8aa3b, v123
	v_exp_f32_e32 v116, v116
	v_exp_f32_e32 v117, v117
	s_lshl_b32 s45, s45, 10
	v_bitop3_b32 v147, v132, s65, v146 bitop3:0xde
	v_add_f32_e32 v116, 1.0, v116
	v_add_f32_e32 v117, 1.0, v117
	v_rcp_f32_e32 v116, v116
	v_rcp_f32_e32 v117, v117
	s_and_b64 vcc, exec, s[42:43]
	s_mov_b32 s68, s44
	s_mov_b32 s69, s46
	v_pk_mul_f32 v[116:117], v[122:123], v[116:117]
	s_mov_b64 s[54:55], s[40:41]
	v_pk_mul_f32 v[116:117], v[116:117], v[118:119]
	v_bitop3_b32 v118, v132, s45, v146 bitop3:0xde
	v_cvt_pk_bf16_f32 v127, v116, v117
	v_mul_f32_e32 v116, 0xbfb8aa3b, v112
	v_mul_f32_e32 v117, 0xbfb8aa3b, v113
	v_exp_f32_e32 v116, v116
	v_exp_f32_e32 v117, v117
	s_or_b32 s45, s5, 32
	s_or_b32 s5, s5, 48
	v_add_f32_e32 v116, 1.0, v116
	v_add_f32_e32 v117, 1.0, v117
	v_rcp_f32_e32 v116, v116
	v_rcp_f32_e32 v117, v117
	s_lshr_b32 s45, s45, 3
	s_lshr_b32 s5, s5, 3
	s_and_b32 s45, s45, 12
	v_pk_mul_f32 v[112:113], v[112:113], v[116:117]
	s_and_b32 s5, s5, 14
	v_pk_mul_f32 v[108:109], v[112:113], v[108:109]
	s_or_b32 s45, s45, s64
	v_cvt_pk_bf16_f32 v108, v108, v109
	v_mul_f32_e32 v109, 0xbfb8aa3b, v114
	v_exp_f32_e32 v109, v109
	s_or_b32 s5, s5, s64
	s_lshl_b32 s45, s45, 10
	s_lshl_b32 s5, s5, 10
	v_add_f32_e32 v109, 1.0, v109
	v_rcp_f32_e32 v112, v109
	v_mul_f32_e32 v109, 0xbfb8aa3b, v115
	v_exp_f32_e32 v109, v109
	global_store_dwordx4 v147, v[124:127], s[50:51]
	v_add_f32_e32 v109, 1.0, v109
	v_rcp_f32_e32 v113, v109
	s_nop 0
	v_pk_mul_f32 v[112:113], v[114:115], v[112:113]
	s_nop 0
	v_pk_mul_f32 v[110:111], v[112:113], v[110:111]
	s_nop 0
	v_cvt_pk_bf16_f32 v109, v110, v111
	v_mul_f32_e32 v110, 0xbfb8aa3b, v104
	v_mul_f32_e32 v111, 0xbfb8aa3b, v105
	v_exp_f32_e32 v110, v110
	v_exp_f32_e32 v111, v111
	v_add_f32_e32 v110, 1.0, v110
	v_add_f32_e32 v111, 1.0, v111
	v_rcp_f32_e32 v110, v110
	v_rcp_f32_e32 v111, v111
	s_nop 0
	v_pk_mul_f32 v[104:105], v[104:105], v[110:111]
	s_nop 0
; __device__ __forceinline__ unsigned cvt_pk_bf16(float lo, float hi) { f32x2 v = {lo, hi}; bf16x2v b = __builtin_convertvector(v, bf16x2v); return __builtin_bit_cast(unsigned, b); }
; __device__ __forceinline__ float silu_f(float x) { return x * __builtin_amdgcn_rcpf(1.f + __expf(-x)); }
;     __device__ __forceinline__ void operator()(const f32x4 (&acc)[2][2][4][2], const Unit& u, int wr, int wc, int fr, int fq) const {
;     ...
;                 bf16_t* rowp = O + img_off(row0 + ai * HALF + m * 16, col0, D_FF / 64);
;                 const f32x4 g0 = acc[ai][0][m][0], g1 = acc[ai][0][m][1], u0 = acc[ai][1][m][0], u1 = acc[ai][1][m][1];
;                 u32x4 w;
;                 w.x = cvt_pk_bf16(silu_f(g0[0]) * u0[0], silu_f(g0[1]) * u0[1]); w.y = cvt_pk_bf16(silu_f(g0[2]) * u0[2], silu_f(g0[3]) * u0[3]);
;                 w.z = cvt_pk_bf16(silu_f(g1[0]) * u1[0], silu_f(g1[1]) * u1[1]); w.w = cvt_pk_bf16(silu_f(g1[2]) * u1[2], silu_f(g1[3]) * u1[3]);
;                 *(u32x4*)rowp = w;
	v_pk_mul_f32 v[100:101], v[104:105], v[100:101]
	s_nop 0
	v_cvt_pk_bf16_f32 v110, v100, v101
	v_mul_f32_e32 v100, 0xbfb8aa3b, v106
	v_mul_f32_e32 v101, 0xbfb8aa3b, v107
	v_exp_f32_e32 v100, v100
	v_exp_f32_e32 v101, v101
	v_add_f32_e32 v100, 1.0, v100
	v_add_f32_e32 v101, 1.0, v101
	v_rcp_f32_e32 v100, v100
	v_rcp_f32_e32 v101, v101
	s_nop 0
	v_pk_mul_f32 v[100:101], v[106:107], v[100:101]
	s_nop 0
	v_pk_mul_f32 v[100:101], v[100:101], v[102:103]
	v_bitop3_b32 v102, v132, s45, v146 bitop3:0xde
	v_cvt_pk_bf16_f32 v111, v100, v101
	v_mul_f32_e32 v100, 0xbfb8aa3b, v96
	v_mul_f32_e32 v101, 0xbfb8aa3b, v97
	v_exp_f32_e32 v100, v100
	v_exp_f32_e32 v101, v101
	global_store_dwordx4 v118, v[108:111], s[50:51]
	v_add_f32_e32 v100, 1.0, v100
	v_add_f32_e32 v101, 1.0, v101
	v_rcp_f32_e32 v100, v100
	v_rcp_f32_e32 v101, v101
	s_nop 0
	v_pk_mul_f32 v[96:97], v[96:97], v[100:101]
	s_nop 0
	v_pk_mul_f32 v[92:93], v[96:97], v[92:93]
	s_nop 0
	v_cvt_pk_bf16_f32 v92, v92, v93
	v_mul_f32_e32 v93, 0xbfb8aa3b, v98
	v_exp_f32_e32 v93, v93
	s_nop 0
	v_add_f32_e32 v93, 1.0, v93
	v_rcp_f32_e32 v96, v93
	v_mul_f32_e32 v93, 0xbfb8aa3b, v99
	v_exp_f32_e32 v93, v93
	s_nop 0
	v_add_f32_e32 v93, 1.0, v93
	v_rcp_f32_e32 v97, v93
	s_nop 0
	v_pk_mul_f32 v[96:97], v[98:99], v[96:97]
	s_nop 0
	v_pk_mul_f32 v[94:95], v[96:97], v[94:95]
	s_nop 0
	v_cvt_pk_bf16_f32 v93, v94, v95
	v_mul_f32_e32 v94, 0xbfb8aa3b, v88
	v_mul_f32_e32 v95, 0xbfb8aa3b, v89
	v_exp_f32_e32 v94, v94
	v_exp_f32_e32 v95, v95
	v_add_f32_e32 v94, 1.0, v94
	v_add_f32_e32 v95, 1.0, v95
	v_rcp_f32_e32 v94, v94
	v_rcp_f32_e32 v95, v95
	s_nop 0
	v_pk_mul_f32 v[88:89], v[88:89], v[94:95]
	s_nop 0
	v_pk_mul_f32 v[84:85], v[88:89], v[84:85]
	s_nop 0
	v_cvt_pk_bf16_f32 v94, v84, v85
	v_mul_f32_e32 v84, 0xbfb8aa3b, v90
	v_mul_f32_e32 v85, 0xbfb8aa3b, v91
	v_exp_f32_e32 v84, v84
	v_exp_f32_e32 v85, v85
	v_add_f32_e32 v84, 1.0, v84
	v_add_f32_e32 v85, 1.0, v85
	v_rcp_f32_e32 v84, v84
	v_rcp_f32_e32 v85, v85
	s_nop 0
	v_pk_mul_f32 v[84:85], v[90:91], v[84:85]
	s_nop 0
	v_pk_mul_f32 v[84:85], v[84:85], v[86:87]
	v_bitop3_b32 v86, v132, s5, v146 bitop3:0xde
	v_cvt_pk_bf16_f32 v95, v84, v85
	v_mul_f32_e32 v84, 0xbfb8aa3b, v80
	v_mul_f32_e32 v85, 0xbfb8aa3b, v81
	v_exp_f32_e32 v84, v84
	v_exp_f32_e32 v85, v85
	global_store_dwordx4 v102, v[92:95], s[50:51]
	v_add_f32_e32 v84, 1.0, v84
	v_add_f32_e32 v85, 1.0, v85
	v_rcp_f32_e32 v84, v84
	v_rcp_f32_e32 v85, v85
	s_nop 0
	v_pk_mul_f32 v[80:81], v[80:81], v[84:85]
	s_nop 0
	v_pk_mul_f32 v[76:77], v[80:81], v[76:77]
	s_nop 0
	v_cvt_pk_bf16_f32 v76, v76, v77
	v_mul_f32_e32 v77, 0xbfb8aa3b, v82
	v_exp_f32_e32 v77, v77
	s_nop 0
	v_add_f32_e32 v77, 1.0, v77
	v_rcp_f32_e32 v80, v77
	v_mul_f32_e32 v77, 0xbfb8aa3b, v83
	v_exp_f32_e32 v77, v77
	s_nop 0
	v_add_f32_e32 v77, 1.0, v77
	v_rcp_f32_e32 v81, v77
	s_nop 0
	v_pk_mul_f32 v[80:81], v[82:83], v[80:81]
	s_nop 0
	v_pk_mul_f32 v[78:79], v[80:81], v[78:79]
	s_nop 0
	v_cvt_pk_bf16_f32 v77, v78, v79
	v_mul_f32_e32 v78, 0xbfb8aa3b, v72
	v_mul_f32_e32 v79, 0xbfb8aa3b, v73
	v_exp_f32_e32 v78, v78
	v_exp_f32_e32 v79, v79
	v_add_f32_e32 v78, 1.0, v78
	v_add_f32_e32 v79, 1.0, v79
	v_rcp_f32_e32 v78, v78
	v_rcp_f32_e32 v79, v79
	s_nop 0
	v_pk_mul_f32 v[72:73], v[72:73], v[78:79]
	s_nop 0
	v_pk_mul_f32 v[68:69], v[72:73], v[68:69]
	v_mul_f32_e32 v73, 0xbfb8aa3b, v65
	v_cvt_pk_bf16_f32 v78, v68, v69
	v_mul_f32_e32 v68, 0xbfb8aa3b, v74
	v_mul_f32_e32 v69, 0xbfb8aa3b, v75
	v_exp_f32_e32 v68, v68
	v_exp_f32_e32 v69, v69
	v_exp_f32_e32 v73, v73
	v_add_f32_e32 v68, 1.0, v68
	v_add_f32_e32 v69, 1.0, v69
	v_rcp_f32_e32 v68, v68
	v_rcp_f32_e32 v69, v69
	v_add_f32_e32 v73, 1.0, v73
	v_rcp_f32_e32 v73, v73
	v_pk_mul_f32 v[68:69], v[74:75], v[68:69]
	s_nop 0
	v_pk_mul_f32 v[68:69], v[68:69], v[70:71]
	v_add_u32_e32 v70, 0x80, v145
	v_lshlrev_b32_e32 v71, 6, v70
	v_lshlrev_b32_e32 v72, 2, v70
	v_and_or_b32 v71, v71, s15, v142
	v_and_b32_e32 v72, 32, v72
	v_bitop3_b32 v132, v71, s65, v72 bitop3:0xde
	v_mul_f32_e32 v72, 0xbfb8aa3b, v64
	v_exp_f32_e32 v72, v72
	v_cvt_pk_bf16_f32 v79, v68, v69
	v_lshrrev_b32_e32 v68, 8, v70
	v_mov_b32_e32 v69, s4
	v_add_f32_e32 v72, 1.0, v72
	v_rcp_f32_e32 v72, v72
	s_movk_i32 s4, 0x58
	v_mad_i32_i24 v68, v68, s4, v69
	v_ashrrev_i32_e32 v69, 31, v68
	v_pk_mul_f32 v[64:65], v[64:65], v[72:73]
	v_lshlrev_b64 v[68:69], 15, v[68:69]
	v_pk_mul_f32 v[60:61], v[64:65], v[60:61]
	v_lshlrev_b32_e32 v70, 7, v70
	v_cvt_pk_bf16_f32 v60, v60, v61
	v_mul_f32_e32 v61, 0xbfb8aa3b, v66
	v_exp_f32_e32 v61, v61
	v_lshl_add_u64 v[68:69], s[16:17], 0, v[68:69]
	v_and_b32_e32 v70, 0x4000, v70
	v_mov_b32_e32 v71, v133
	v_add_f32_e32 v61, 1.0, v61
	v_rcp_f32_e32 v64, v61
	v_mul_f32_e32 v61, 0xbfb8aa3b, v67
	v_exp_f32_e32 v61, v61
	v_lshl_add_u64 v[70:71], v[68:69], 0, v[70:71]
	v_lshl_add_u64 v[70:71], v[70:71], 0, v[132:133]
	s_mov_b64 s[4:5], s[48:49]
	v_add_f32_e32 v61, 1.0, v61
	v_rcp_f32_e32 v65, v61
	global_store_dwordx4 v86, v[76:79], s[50:51]
	v_pk_mul_f32 v[64:65], v[66:67], v[64:65]
	s_nop 0
	v_pk_mul_f32 v[62:63], v[64:65], v[62:63]
	s_nop 0
	v_cvt_pk_bf16_f32 v61, v62, v63
	v_mul_f32_e32 v62, 0xbfb8aa3b, v56
	v_mul_f32_e32 v63, 0xbfb8aa3b, v57
	v_exp_f32_e32 v62, v62
	v_exp_f32_e32 v63, v63
	v_add_f32_e32 v62, 1.0, v62
	v_add_f32_e32 v63, 1.0, v63
	v_rcp_f32_e32 v62, v62
	v_rcp_f32_e32 v63, v63
	s_nop 0
	v_pk_mul_f32 v[56:57], v[56:57], v[62:63]
	s_nop 0
	v_pk_mul_f32 v[52:53], v[56:57], v[52:53]
	s_nop 0
	v_cvt_pk_bf16_f32 v62, v52, v53
	v_mul_f32_e32 v52, 0xbfb8aa3b, v58
	v_mul_f32_e32 v53, 0xbfb8aa3b, v59
	v_exp_f32_e32 v52, v52
	v_exp_f32_e32 v53, v53
	v_add_f32_e32 v52, 1.0, v52
	v_add_f32_e32 v53, 1.0, v53
	v_rcp_f32_e32 v52, v52
; __device__ __forceinline__ unsigned cvt_pk_bf16(float lo, float hi) { f32x2 v = {lo, hi}; bf16x2v b = __builtin_convertvector(v, bf16x2v); return __builtin_bit_cast(unsigned, b); }
; __device__ __forceinline__ float silu_f(float x) { return x * __builtin_amdgcn_rcpf(1.f + __expf(-x)); }
; #define PG8_WAIT_V(n) asm volatile("s_waitcnt vmcnt(" #n ")" ::: "memory")
; #define PG8_BAR __builtin_amdgcn_s_barrier()
;     __device__ __forceinline__ void operator()(const f32x4 (&acc)[2][2][4][2], const Unit& u, int wr, int wc, int fr, int fq) const {
;     ...
;                 bf16_t* rowp = O + img_off(row0 + ai * HALF + m * 16, col0, D_FF / 64);
;                 const f32x4 g0 = acc[ai][0][m][0], g1 = acc[ai][0][m][1], u0 = acc[ai][1][m][0], u1 = acc[ai][1][m][1];
;                 u32x4 w;
;                 w.x = cvt_pk_bf16(silu_f(g0[0]) * u0[0], silu_f(g0[1]) * u0[1]); w.y = cvt_pk_bf16(silu_f(g0[2]) * u0[2], silu_f(g0[3]) * u0[3]);
;                 w.z = cvt_pk_bf16(silu_f(g1[0]) * u1[0], silu_f(g1[1]) * u1[1]); w.w = cvt_pk_bf16(silu_f(g1[2]) * u1[2], silu_f(g1[3]) * u1[3]);
;                 *(u32x4*)rowp = w;
; template <class Epi, class Sched, int LD>
; __device__ __forceinline__ void gemm_phase(LAS unsigned char* lds, const Gemm g, const Sched& S, const Epi& E) {
;     ...
;     PG8_WAIT_V(0);
;     if (wr == 0) PG8_BAR;
;     PG8_BAR;
	v_rcp_f32_e32 v53, v53
	s_nop 0
	v_pk_mul_f32 v[52:53], v[58:59], v[52:53]
	s_nop 0
	v_pk_mul_f32 v[52:53], v[52:53], v[54:55]
	s_nop 0
	v_cvt_pk_bf16_f32 v63, v52, v53
	v_add_u32_e32 v52, 0x90, v145
	v_lshrrev_b32_e32 v54, 3, v52
	v_lshlrev_b32_e32 v53, 6, v52
	v_and_or_b32 v54, v54, 10, s64
	v_lshlrev_b32_e32 v55, 2, v52
	v_and_or_b32 v53, v53, s15, v142
	v_lshlrev_b32_e32 v54, 10, v54
	v_and_b32_e32 v55, 32, v55
	v_bitop3_b32 v132, v53, v54, v55 bitop3:0xde
	v_mul_f32_e32 v54, 0xbfb8aa3b, v48
	v_mul_f32_e32 v55, 0xbfb8aa3b, v49
	v_exp_f32_e32 v54, v54
	v_exp_f32_e32 v55, v55
	v_lshlrev_b32_e32 v52, 7, v52
	v_and_b32_e32 v52, 0x4000, v52
	v_add_f32_e32 v54, 1.0, v54
	v_add_f32_e32 v55, 1.0, v55
	v_rcp_f32_e32 v54, v54
	v_rcp_f32_e32 v55, v55
	v_mov_b32_e32 v53, v133
	v_lshl_add_u64 v[52:53], v[68:69], 0, v[52:53]
	v_lshl_add_u64 v[52:53], v[52:53], 0, v[132:133]
	v_pk_mul_f32 v[48:49], v[48:49], v[54:55]
	global_store_dwordx4 v[70:71], v[60:63], off
	v_pk_mul_f32 v[44:45], v[48:49], v[44:45]
	s_nop 0
	v_cvt_pk_bf16_f32 v44, v44, v45
	v_mul_f32_e32 v45, 0xbfb8aa3b, v50
	v_exp_f32_e32 v45, v45
	s_nop 0
	v_add_f32_e32 v45, 1.0, v45
	v_rcp_f32_e32 v48, v45
	v_mul_f32_e32 v45, 0xbfb8aa3b, v51
	v_exp_f32_e32 v45, v45
	s_nop 0
	v_add_f32_e32 v45, 1.0, v45
	v_rcp_f32_e32 v49, v45
	s_nop 0
	v_pk_mul_f32 v[48:49], v[50:51], v[48:49]
	s_nop 0
	v_pk_mul_f32 v[46:47], v[48:49], v[46:47]
	s_nop 0
	v_cvt_pk_bf16_f32 v45, v46, v47
	v_mul_f32_e32 v46, 0xbfb8aa3b, v40
	v_mul_f32_e32 v47, 0xbfb8aa3b, v41
	v_exp_f32_e32 v46, v46
	v_exp_f32_e32 v47, v47
	v_add_f32_e32 v46, 1.0, v46
	v_add_f32_e32 v47, 1.0, v47
	v_rcp_f32_e32 v46, v46
	v_rcp_f32_e32 v47, v47
	s_nop 0
	v_pk_mul_f32 v[40:41], v[40:41], v[46:47]
	s_nop 0
	v_pk_mul_f32 v[36:37], v[40:41], v[36:37]
	s_nop 0
	v_cvt_pk_bf16_f32 v46, v36, v37
	v_mul_f32_e32 v36, 0xbfb8aa3b, v42
	v_mul_f32_e32 v37, 0xbfb8aa3b, v43
	v_exp_f32_e32 v36, v36
	v_exp_f32_e32 v37, v37
	v_add_f32_e32 v36, 1.0, v36
	v_add_f32_e32 v37, 1.0, v37
	v_rcp_f32_e32 v36, v36
	v_rcp_f32_e32 v37, v37
	s_nop 0
	v_pk_mul_f32 v[36:37], v[42:43], v[36:37]
	s_nop 0
	v_pk_mul_f32 v[36:37], v[36:37], v[38:39]
	s_nop 0
	v_cvt_pk_bf16_f32 v47, v36, v37
	v_add_u32_e32 v36, 0xa0, v145
	v_lshrrev_b32_e32 v38, 3, v36
	v_lshlrev_b32_e32 v37, 6, v36
	v_and_or_b32 v38, v38, 12, s64
	v_lshlrev_b32_e32 v39, 2, v36
	v_and_or_b32 v37, v37, s15, v142
	v_lshlrev_b32_e32 v38, 10, v38
	v_and_b32_e32 v39, 32, v39
	v_bitop3_b32 v132, v37, v38, v39 bitop3:0xde
	v_mul_f32_e32 v38, 0xbfb8aa3b, v32
	v_mul_f32_e32 v39, 0xbfb8aa3b, v33
	v_exp_f32_e32 v38, v38
	v_exp_f32_e32 v39, v39
	v_lshlrev_b32_e32 v36, 7, v36
	v_and_b32_e32 v36, 0x4000, v36
	v_add_f32_e32 v38, 1.0, v38
	v_add_f32_e32 v39, 1.0, v39
	v_rcp_f32_e32 v38, v38
	v_rcp_f32_e32 v39, v39
	v_mov_b32_e32 v37, v133
	v_lshl_add_u64 v[36:37], v[68:69], 0, v[36:37]
	v_lshl_add_u64 v[36:37], v[36:37], 0, v[132:133]
	v_pk_mul_f32 v[32:33], v[32:33], v[38:39]
	global_store_dwordx4 v[52:53], v[44:47], off
	v_pk_mul_f32 v[28:29], v[32:33], v[28:29]
	s_nop 0
	v_cvt_pk_bf16_f32 v28, v28, v29
	v_mul_f32_e32 v29, 0xbfb8aa3b, v34
	v_exp_f32_e32 v29, v29
	s_nop 0
	v_add_f32_e32 v29, 1.0, v29
	v_rcp_f32_e32 v32, v29
	v_mul_f32_e32 v29, 0xbfb8aa3b, v35
	v_exp_f32_e32 v29, v29
	s_nop 0
	v_add_f32_e32 v29, 1.0, v29
	v_rcp_f32_e32 v33, v29
	s_nop 0
	v_pk_mul_f32 v[32:33], v[34:35], v[32:33]
	s_nop 0
	v_pk_mul_f32 v[30:31], v[32:33], v[30:31]
	s_nop 0
	v_cvt_pk_bf16_f32 v29, v30, v31
	v_mul_f32_e32 v30, 0xbfb8aa3b, v24
	v_mul_f32_e32 v31, 0xbfb8aa3b, v25
	v_exp_f32_e32 v30, v30
	v_exp_f32_e32 v31, v31
	v_add_f32_e32 v30, 1.0, v30
	v_add_f32_e32 v31, 1.0, v31
	v_rcp_f32_e32 v30, v30
	v_rcp_f32_e32 v31, v31
	s_nop 0
	v_pk_mul_f32 v[24:25], v[24:25], v[30:31]
	s_nop 0
	v_pk_mul_f32 v[20:21], v[24:25], v[20:21]
	s_nop 0
	v_cvt_pk_bf16_f32 v30, v20, v21
	v_mul_f32_e32 v20, 0xbfb8aa3b, v26
	v_mul_f32_e32 v21, 0xbfb8aa3b, v27
	v_exp_f32_e32 v20, v20
	v_exp_f32_e32 v21, v21
	v_add_f32_e32 v20, 1.0, v20
	v_add_f32_e32 v21, 1.0, v21
	v_rcp_f32_e32 v20, v20
	v_rcp_f32_e32 v21, v21
	s_nop 0
	v_pk_mul_f32 v[20:21], v[26:27], v[20:21]
	s_nop 0
	v_pk_mul_f32 v[20:21], v[20:21], v[22:23]
	s_nop 0
	v_cvt_pk_bf16_f32 v31, v20, v21
	v_add_u32_e32 v20, 0xb0, v145
	v_lshrrev_b32_e32 v22, 3, v20
	v_lshlrev_b32_e32 v21, 6, v20
	v_and_or_b32 v22, v22, 14, s64
	v_lshlrev_b32_e32 v23, 2, v20
	v_and_or_b32 v21, v21, s15, v142
	v_lshlrev_b32_e32 v22, 10, v22
	v_and_b32_e32 v23, 32, v23
	v_bitop3_b32 v132, v21, v22, v23 bitop3:0xde
	v_mul_f32_e32 v22, 0xbfb8aa3b, v16
	v_mul_f32_e32 v23, 0xbfb8aa3b, v17
	v_exp_f32_e32 v22, v22
	v_exp_f32_e32 v23, v23
	v_lshlrev_b32_e32 v20, 7, v20
	v_and_b32_e32 v20, 0x4000, v20
	v_add_f32_e32 v22, 1.0, v22
	v_add_f32_e32 v23, 1.0, v23
	v_rcp_f32_e32 v22, v22
	v_rcp_f32_e32 v23, v23
	v_mov_b32_e32 v21, v133
	v_lshl_add_u64 v[20:21], v[68:69], 0, v[20:21]
	v_lshl_add_u64 v[20:21], v[20:21], 0, v[132:133]
	v_pk_mul_f32 v[16:17], v[16:17], v[22:23]
	global_store_dwordx4 v[36:37], v[28:31], off
	v_pk_mul_f32 v[12:13], v[16:17], v[12:13]
	s_nop 0
	v_cvt_pk_bf16_f32 v12, v12, v13
	v_mul_f32_e32 v13, 0xbfb8aa3b, v18
	v_exp_f32_e32 v13, v13
	s_nop 0
	v_add_f32_e32 v13, 1.0, v13
	v_rcp_f32_e32 v16, v13
	v_mul_f32_e32 v13, 0xbfb8aa3b, v19
	v_exp_f32_e32 v13, v13
	s_nop 0
	v_add_f32_e32 v13, 1.0, v13
	v_rcp_f32_e32 v17, v13
	s_nop 0
	v_pk_mul_f32 v[16:17], v[18:19], v[16:17]
	s_nop 0
	v_pk_mul_f32 v[14:15], v[16:17], v[14:15]
	s_nop 0
	v_cvt_pk_bf16_f32 v13, v14, v15
	v_mul_f32_e32 v14, 0xbfb8aa3b, v8
	v_mul_f32_e32 v15, 0xbfb8aa3b, v9
	v_exp_f32_e32 v14, v14
	v_exp_f32_e32 v15, v15
	v_add_f32_e32 v14, 1.0, v14
	v_add_f32_e32 v15, 1.0, v15
	v_rcp_f32_e32 v14, v14
	v_rcp_f32_e32 v15, v15
	s_nop 0
	v_pk_mul_f32 v[8:9], v[8:9], v[14:15]
	s_nop 0
	v_pk_mul_f32 v[4:5], v[8:9], v[4:5]
	s_nop 0
	v_cvt_pk_bf16_f32 v14, v4, v5
	v_mul_f32_e32 v4, 0xbfb8aa3b, v10
	v_mul_f32_e32 v5, 0xbfb8aa3b, v11
	v_exp_f32_e32 v4, v4
	v_exp_f32_e32 v5, v5
	v_add_f32_e32 v4, 1.0, v4
	v_add_f32_e32 v5, 1.0, v5
	v_rcp_f32_e32 v4, v4
	v_rcp_f32_e32 v5, v5
	s_nop 0
	v_pk_mul_f32 v[4:5], v[10:11], v[4:5]
	s_nop 0
	v_pk_mul_f32 v[4:5], v[4:5], v[6:7]
	s_nop 0
	v_cvt_pk_bf16_f32 v15, v4, v5
	global_store_dwordx4 v[20:21], v[12:15], off
	s_cbranch_vccz .LBB0_892
	s_waitcnt vmcnt(0)
	s_cmpk_gt_u32 s2, 0xff
	s_cbranch_scc1 .LBB0_903
	s_barrier
